# FoX prompt unit: O accumulator kept loop-carried in v[20:51] (pending P.V accumulates there), removing 32 v_mov_b64 + hazard nops per 128-key trip
# speedup vs baseline: 1.0155x; 1.0155x over previous
; #define LAS __attribute__((address_space(3)))
; __device__ __forceinline__ void conv_load(ConvRegs& c, const Args& a, size_t rowq, int col, int lane) {
; #pragma unroll
;     for (int i = 0; i < 4; ++i) { const size_t grow = rowq + i * 8 + (lane >> 3);
; __device__ __forceinline__ void prompt_unit_fox(const Args& a, int l, int b, int h, int qb, LAS unsigned char* lds) {
;     int tid_ = threadIdx.x; asm volatile("" : "+v"(tid_));
;     const int tid = tid_, lane = tid & 63, r32 = lane & 31, hi = lane >> 5, wid = __builtin_amdgcn_readfirstlane(tid >> 6);
;     const int q0 = qb * 256, NP = (q0 + 256) / 128, jd = q0 / 64 + (wid >> 1), jpd = jd >> 1;
;     const bool lateB = wid >= 4;
;     const int col = h * HD;
;     const size_t rowb = (size_t)b * T;
;     const bf16* Kh = (const bf16*)(a.ws + WS_K) + rowb * D + col; const bf16* Vh = (const bf16*)(a.ws + WS_V) + rowb * D + col;
;     const unsigned lds0 = (unsigned)(uintptr_t)lds;
;     const bf16* ksrc = Kh + (size_t)lane * D + wid * 8;
;     const bf16* vsrc = Vh + (size_t)(16 * (wid & 3) + (lane >> 2)) * D + (wid >> 2) * 32 + (lane & 3) * 8;
;     ...
;     ATT_DMA2(NP - 1, 0);
;     { const int idx = tid * 4; if (idx < q0 + 256) { const f32x4 c = *(const f32x4*)((const float*)(a.ws + WS_CKP) + (size_t)(b * 8 + h) * T + idx); *(LAS f32x4*)(lds + F_CK + idx * 4) = c;
; #pragma unroll
;         for (int e = 0; e < 4; ++e) { const float h1 = bf_hi_part(c[e]), r1 = c[e] - h1, h2 = bf_hi_part(r1), r2 = r1 - h2; ((LAS u32x2*)(lds + F_AUG))[idx + e] = (u32x2){cvtpk(h1, h2), cvtpk(r2, -1.0f)}; } } }
;     bf16x8 qr[4];
;     { const bf16* Qw = (const bf16*)(a.ws + WS_Q) + (rowb + q0 + wid * 32 + r32) * D + col;
; #pragma unroll
;       for (int d0 = 0; d0 < 4; ++d0) qr[d0] = *(const bf16x8*)(Qw + d0 * 16 + hi * 8); }
;     const lds_cptr vp0 = (lds_cptr)lds + F_V + ((lane >> 4) & 1) * 32 + (lane & 3) * 8 + (4 * hi + ((lane & 15) >> 2)) * 64;
;     const int ql = 32 * (wid & 1) + r32, qlim = ql + 1;
;     LAS float* wsf = (LAS float*)(lds + F_WSF) + wid * 64;
;     FoxState st; st.m = 0.f; st.l = 0.f; st.mq = (bf16x8){}; st.o[0] = (f32x16){}; st.o[1] = (f32x16){};
;     PairP pp; bool pending = false;
; #pragma unroll
;     for (int i = 0; i < 8; ++i) pp.w[i] = (u32x4){0u, 0u, 0u, 0u};
;     { ConvRegs cv; conv_load(cv, a, rowb + q0 + wid * 32, col, lane); conv_store<0>(cv, a, l, h, rowb + q0 + wid * 32, lane); }
.LBB0_311:
	s_or_b64 exec, exec, s[0:1]
	s_lshl_b32 s0, s6, 2
	s_ashr_i32 s1, s3, 7
	s_add_i32 s1, s1, s0
	s_ashr_i32 s89, s1, 1
	s_cmp_lt_i32 s77, 4
	s_cselect_b64 s[92:93], -1, 0
	s_lshl_b32 s0, s5, 11
	s_lshl_b32 s5, s77, 5
	s_or_b32 s0, s7, s0
	s_ashr_i32 s1, s5, 31
	s_add_u32 s91, s5, s0
	v_and_b32_e32 v175, 31, v19
	s_addc_u32 s0, s1, 0
	v_or_b32_e32 v168, s91, v175
	v_mov_b32_e32 v169, s0
	v_lshrrev_b32_e32 v1, 3, v20
	v_lshlrev_b64 v[2:3], 11, v[168:169]
	v_or_b32_e32 v168, s91, v1
	v_lshlrev_b32_e32 v4, 3, v20
	v_lshlrev_b64 v[170:171], 11, v[168:169]
	s_lshl_b32 s74, s4, 1
	s_mov_b32 s75, s87
	v_and_b32_e32 v174, 56, v4
	v_lshl_add_u64 v[8:9], s[94:95], 0, v[170:171]
	v_lshl_add_u64 v[8:9], v[8:9], 0, s[74:75]
	v_mov_b32_e32 v4, v174
	v_readlane_b32 s6, v242, 20
	v_lshl_add_u64 v[8:9], v[8:9], 0, v[4:5]
	v_readlane_b32 s7, v242, 21
	global_load_dwordx2 v[24:25], v[8:9], off offset:64
	global_load_dwordx2 v[22:23], v[8:9], off
	v_or_b32_e32 v58, 0x4000, v170
	v_lshl_add_u64 v[8:9], s[6:7], 0, v[170:171]
	v_lshl_add_u64 v[8:9], v[8:9], 0, s[74:75]
	v_lshl_add_u64 v[8:9], v[8:9], 0, v[4:5]
	v_mov_b32_e32 v59, v171
	global_load_dwordx2 v[28:29], v[8:9], off offset:64
	global_load_dwordx2 v[26:27], v[8:9], off
	v_lshl_add_u64 v[8:9], s[94:95], 0, v[58:59]
	v_lshl_add_u64 v[8:9], v[8:9], 0, s[74:75]
	v_lshl_add_u64 v[8:9], v[8:9], 0, v[4:5]
	global_load_dwordx2 v[32:33], v[8:9], off offset:64
	global_load_dwordx2 v[30:31], v[8:9], off
	v_lshl_add_u64 v[8:9], s[6:7], 0, v[58:59]
	v_lshrrev_b32_e32 v21, 5, v20
	v_lshl_add_u64 v[8:9], v[8:9], 0, s[74:75]
	v_lshlrev_b32_e32 v7, 1, v19
	v_lshrrev_b32_e32 v10, 2, v19
	v_lshlrev_b32_e32 v66, 2, v21
	v_lshl_add_u64 v[8:9], v[8:9], 0, v[4:5]
	v_and_b32_e32 v7, 32, v7
	global_load_dwordx2 v[36:37], v[8:9], off offset:64
	global_load_dwordx2 v[34:35], v[8:9], off
	v_and_or_b32 v8, v10, 3, v66
	v_add_u32_e32 v7, 0, v7
	v_lshlrev_b32_e32 v8, 6, v8
	v_or_b32_e32 v60, 0x8000, v170
	v_mov_b32_e32 v61, v171
	v_add3_u32 v180, v7, v6, v8
	v_lshl_add_u64 v[6:7], s[94:95], 0, v[60:61]
	v_and_or_b32 v67, s5, 32, v175
	s_and_b32 s5, s3, 0x3fffffc0
	v_lshl_add_u64 v[6:7], v[6:7], 0, s[74:75]
	v_writelane_b32 v237, s0, 11
	s_lshl_b32 s0, s4, 2
	s_lshl_b32 s4, s5, 2
	v_lshl_add_u64 v[6:7], v[6:7], 0, v[4:5]
	v_lshl_add_u64 v[10:11], s[6:7], 0, v[60:61]
	s_add_i32 s78, s4, 0
	v_readlane_b32 s4, v242, 22
	global_load_dwordx2 v[40:41], v[6:7], off offset:64
	global_load_dwordx2 v[38:39], v[6:7], off
	v_lshl_add_u64 v[10:11], v[10:11], 0, s[74:75]
	v_readlane_b32 s5, v242, 23
	v_lshl_add_u64 v[10:11], v[10:11], 0, v[4:5]
	v_readlane_b32 s8, v242, 45
	v_lshl_add_u64 v[2:3], s[4:5], 0, v[2:3]
	v_readlane_b32 s4, v242, 43
	global_load_dwordx2 v[44:45], v[10:11], off offset:64
	global_load_dwordx2 v[42:43], v[10:11], off
	v_mov_b32_e32 v173, v5
	v_lshlrev_b32_e32 v172, 4, v21
	v_lshl_add_u64 v[2:3], v[2:3], 0, s[74:75]
	v_or_b32_e32 v62, 0xc000, v170
	v_mov_b32_e32 v63, v171
	v_readlane_b32 s5, v242, 44
	v_readlane_b32 s9, v242, 46
	s_mov_b32 s1, s87
	v_lshl_add_u64 v[6:7], s[4:5], 0, v[170:171]
	v_lshl_add_u64 v[8:9], s[8:9], 0, v[170:171]
	v_lshl_add_u64 v[2:3], v[2:3], 0, v[172:173]
	v_lshl_add_u64 v[46:47], s[94:95], 0, v[62:63]
	v_lshl_add_u64 v[48:49], s[6:7], 0, v[62:63]
	v_lshl_add_u64 v[54:55], v[6:7], 0, s[0:1]
	v_lshl_add_u64 v[56:57], v[8:9], 0, s[0:1]
	global_load_dwordx4 v[6:9], v[2:3], off
	global_load_dwordx4 v[10:13], v[2:3], off offset:32
	global_load_dwordx4 v[14:17], v[2:3], off offset:64
	global_load_dwordx4 v[116:119], v[2:3], off offset:96
	v_lshl_add_u64 v[2:3], v[46:47], 0, s[74:75]
	v_lshl_add_u64 v[46:47], v[48:49], 0, s[74:75]
	v_lshl_add_u64 v[2:3], v[2:3], 0, v[4:5]
	v_lshl_add_u64 v[50:51], v[46:47], 0, v[4:5]
	global_load_dwordx2 v[48:49], v[2:3], off offset:64
	global_load_dwordx2 v[46:47], v[2:3], off
	s_nop 0
	global_load_dwordx2 v[52:53], v[50:51], off offset:64
	global_load_dwordx2 v[50:51], v[50:51], off
	v_lshlrev_b32_e32 v4, 1, v174
	v_lshl_add_u64 v[2:3], v[54:55], 0, v[4:5]
	v_lshl_add_u64 v[64:65], v[56:57], 0, v[4:5]
	s_add_i32 s78, s78, 0x1a000
	v_cmp_lt_u32_e64 s[12:13], v66, v67
	v_cmp_gt_u32_e64 s[6:7], 32, v20
	v_lshlrev_b32_e32 v173, 10, v21
	v_lshlrev_b32_e32 v188, 4, v175
	v_cndmask_b32_e64 v122, 0, v185, s[6:7]
	v_cndmask_b32_e64 v121, 0, -1.0, s[6:7]
	v_mov_b32_e32 v120, v5
	v_mov_b32_e32 v123, v5
	v_lshl_add_u32 v182, v175, 2, s78
	v_mov_b32_e32 v156, v5
	s_waitcnt vmcnt(0)
; __device__ __forceinline__ float bflo(unsigned w) { return __uint_as_float(w << 16); }
; __device__ __forceinline__ float bfhi(unsigned w) { return __uint_as_float(w & 0xffff0000u); }
; template <int TYPE>
; __device__ __forceinline__ void conv_store(const ConvRegs& c, const Args& a, int l, int h, size_t rowq, int lane) {
; #pragma unroll
;     for (int i = 0; i < 4; ++i) { const size_t grow = rowq + i * 8 + (lane >> 3);
;         float* ko = a.out + (TYPE == 0 ? O_FKP : O_SKP) + ((size_t)l * MP + grow) * W + h * HD + (lane & 7) * 8;
;         float* vo = a.out + (TYPE == 0 ? O_FVP : O_SVP) + ((size_t)l * MP + grow) * W + h * HD + (lane & 7) * 8;
;         const u32x4 kw = c.k[i], vw = c.v[i];
;         __builtin_nontemporal_store((f32x4){bflo(kw.x), bfhi(kw.x), bflo(kw.y), bfhi(kw.y)}, (f32x4*)ko); __builtin_nontemporal_store((f32x4){bflo(kw.z), bfhi(kw.z), bflo(kw.w), bfhi(kw.w)}, (f32x4*)(ko + 4));
;         __builtin_nontemporal_store((f32x4){bflo(vw.x), bfhi(vw.x), bflo(vw.y), bfhi(vw.y)}, (f32x4*)vo); __builtin_nontemporal_store((f32x4){bflo(vw.z), bfhi(vw.z), bflo(vw.w), bfhi(vw.w)}, (f32x4*)(vo + 4)); }
; }
	v_lshlrev_b32_e32 v54, 16, v22
	v_and_b32_e32 v55, 0xffff0000, v22
	v_lshlrev_b32_e32 v56, 16, v23
	v_and_b32_e32 v57, 0xffff0000, v23
	v_lshlrev_b32_e32 v22, 16, v24
	v_and_b32_e32 v23, 0xffff0000, v24
	v_lshlrev_b32_e32 v24, 16, v25
	v_and_b32_e32 v25, 0xffff0000, v25
	global_store_dwordx4 v[2:3], v[22:25], off offset:128
	global_store_dwordx4 v[2:3], v[54:57], off
	v_lshl_add_u64 v[2:3], s[4:5], 0, v[58:59]
	v_lshlrev_b32_e32 v22, 16, v26
	v_and_b32_e32 v23, 0xffff0000, v26
	v_lshlrev_b32_e32 v24, 16, v27
	v_and_b32_e32 v25, 0xffff0000, v27
	global_store_dwordx4 v[64:65], v[22:25], off
	v_lshl_add_u64 v[2:3], v[2:3], 0, s[0:1]
	v_lshl_add_u64 v[2:3], v[2:3], 0, v[4:5]
	v_lshlrev_b32_e32 v22, 16, v28
	v_and_b32_e32 v23, 0xffff0000, v28
	v_lshlrev_b32_e32 v24, 16, v29
	v_and_b32_e32 v25, 0xffff0000, v29
	global_store_dwordx4 v[64:65], v[22:25], off offset:128
	v_mov_b32_e32 v54, v5
	v_mov_b32_e32 v55, v5
	v_lshl_add_u64 v[22:23], s[8:9], 0, v[58:59]
	v_lshl_add_u64 v[22:23], v[22:23], 0, s[0:1]
	v_lshl_add_u64 v[26:27], v[22:23], 0, v[4:5]
	v_lshlrev_b32_e32 v22, 16, v30
	v_and_b32_e32 v23, 0xffff0000, v30
	v_lshlrev_b32_e32 v24, 16, v31
	v_and_b32_e32 v25, 0xffff0000, v31
	global_store_dwordx4 v[2:3], v[22:25], off
	v_mov_b32_e32 v56, v5
	v_mov_b32_e32 v57, v5
	v_lshlrev_b32_e32 v22, 16, v32
	v_and_b32_e32 v23, 0xffff0000, v32
	v_lshlrev_b32_e32 v24, 16, v33
	v_and_b32_e32 v25, 0xffff0000, v33
	global_store_dwordx4 v[2:3], v[22:25], off offset:128
	v_lshl_add_u64 v[2:3], s[4:5], 0, v[60:61]
	v_lshl_add_u64 v[2:3], v[2:3], 0, s[0:1]
	v_lshlrev_b32_e32 v22, 16, v34
	v_and_b32_e32 v23, 0xffff0000, v34
	v_lshlrev_b32_e32 v24, 16, v35
	v_and_b32_e32 v25, 0xffff0000, v35
	global_store_dwordx4 v[26:27], v[22:25], off
	v_lshl_add_u64 v[2:3], v[2:3], 0, v[4:5]
	v_mov_b32_e32 v58, v5
	v_lshlrev_b32_e32 v22, 16, v36
	v_and_b32_e32 v23, 0xffff0000, v36
	v_lshlrev_b32_e32 v24, 16, v37
	v_and_b32_e32 v25, 0xffff0000, v37
	global_store_dwordx4 v[26:27], v[22:25], off offset:128
	v_mov_b32_e32 v59, v5
	v_mov_b32_e32 v64, v5
	v_lshl_add_u64 v[22:23], s[8:9], 0, v[60:61]
	v_lshl_add_u64 v[22:23], v[22:23], 0, s[0:1]
	v_lshl_add_u64 v[26:27], v[22:23], 0, v[4:5]
	v_lshlrev_b32_e32 v22, 16, v38
	v_and_b32_e32 v23, 0xffff0000, v38
	v_lshlrev_b32_e32 v24, 16, v39
	v_and_b32_e32 v25, 0xffff0000, v39
	global_store_dwordx4 v[2:3], v[22:25], off
	v_mov_b32_e32 v60, v5
	v_mov_b32_e32 v61, v5
	v_lshlrev_b32_e32 v22, 16, v40
	v_and_b32_e32 v23, 0xffff0000, v40
	v_lshlrev_b32_e32 v24, 16, v41
	v_and_b32_e32 v25, 0xffff0000, v41
	global_store_dwordx4 v[2:3], v[22:25], off offset:128
	v_lshl_add_u64 v[2:3], s[4:5], 0, v[62:63]
	v_lshl_add_u64 v[2:3], v[2:3], 0, s[0:1]
	v_lshlrev_b32_e32 v22, 16, v42
	v_and_b32_e32 v23, 0xffff0000, v42
	v_lshlrev_b32_e32 v24, 16, v43
	v_and_b32_e32 v25, 0xffff0000, v43
	global_store_dwordx4 v[26:27], v[22:25], off
	v_lshl_add_u64 v[2:3], v[2:3], 0, v[4:5]
	v_mov_b32_e32 v65, v5
	v_lshlrev_b32_e32 v22, 16, v44
	v_and_b32_e32 v23, 0xffff0000, v44
	v_lshlrev_b32_e32 v24, 16, v45
	v_and_b32_e32 v25, 0xffff0000, v45
	global_store_dwordx4 v[26:27], v[22:25], off offset:128
	v_mov_b32_e32 v157, v5
	v_mov_b32_e32 v158, v5
	v_lshl_add_u64 v[22:23], s[8:9], 0, v[62:63]
	v_lshl_add_u64 v[22:23], v[22:23], 0, s[0:1]
	v_lshl_add_u64 v[26:27], v[22:23], 0, v[4:5]
	v_lshlrev_b32_e32 v22, 16, v46
	v_and_b32_e32 v23, 0xffff0000, v46
	v_lshlrev_b32_e32 v24, 16, v47
	v_and_b32_e32 v25, 0xffff0000, v47
	global_store_dwordx4 v[2:3], v[22:25], off
	s_add_i32 s1, 0, 0x18000
	v_add_u32_e32 v184, s1, v172
	v_lshlrev_b32_e32 v22, 16, v48
	v_and_b32_e32 v23, 0xffff0000, v48
	v_lshlrev_b32_e32 v24, 16, v49
	v_and_b32_e32 v25, 0xffff0000, v49
	global_store_dwordx4 v[2:3], v[22:25], off offset:128
	v_or_b32_e32 v2, 32, v66
	v_cmp_gt_u32_e64 s[10:11], v2, v67
	v_or_b32_e32 v2, 33, v66
	v_cmp_gt_u32_e64 s[14:15], v2, v67
	v_or_b32_e32 v2, 2, v66
	v_cmp_gt_u32_e64 s[16:17], v2, v67
	v_or_b32_e32 v2, 34, v66
; #define LAS __attribute__((address_space(3)))
; #define ATT_WAIT_BAR() asm volatile("s_waitcnt vmcnt(0) lgkmcnt(0)\n\ts_barrier" ::: "memory")
; __device__ __forceinline__ void prompt_unit_fox(const Args& a, int l, int b, int h, int qb, LAS unsigned char* lds) {
;     ...
;     const lds_cptr vp0 = (lds_cptr)lds + F_V + ((lane >> 4) & 1) * 32 + (lane & 3) * 8 + (4 * hi + ((lane & 15) >> 2)) * 64;
;     const int ql = 32 * (wid & 1) + r32, qlim = ql + 1;
;     LAS float* wsf = (LAS float*)(lds + F_WSF) + wid * 64;
;     FoxState st; st.m = 0.f; st.l = 0.f; st.mq = (bf16x8){}; st.o[0] = (f32x16){}; st.o[1] = (f32x16){};
;     PairP pp; bool pending = false;
; #pragma unroll
;     for (int i = 0; i < 8; ++i) pp.w[i] = (u32x4){0u, 0u, 0u, 0u};
;     { ConvRegs cv; conv_load(cv, a, rowb + q0 + wid * 32, col, lane); conv_store<0>(cv, a, l, h, rowb + q0 + wid * 32, lane); }
;     int slot = 0, pslot = 0;
;     ...
;         ATT_WAIT_BAR();
	v_cmp_gt_u32_e64 s[18:19], v2, v67
	v_or_b32_e32 v2, 3, v66
	v_cmp_gt_u32_e64 s[20:21], v2, v67
	v_or_b32_e32 v2, 35, v66
	v_cmp_gt_u32_e64 s[22:23], v2, v67
	v_or_b32_e32 v2, 8, v66
	v_cmp_gt_u32_e64 s[24:25], v2, v67
	v_or_b32_e32 v2, 40, v66
	v_cmp_gt_u32_e64 s[26:27], v2, v67
	v_or_b32_e32 v2, 9, v66
	v_cmp_gt_u32_e64 s[28:29], v2, v67
	v_or_b32_e32 v2, 41, v66
	v_cmp_gt_u32_e64 s[30:31], v2, v67
	v_or_b32_e32 v2, 10, v66
	v_cmp_gt_u32_e64 s[34:35], v2, v67
	v_or_b32_e32 v2, 42, v66
	v_cmp_gt_u32_e64 s[36:37], v2, v67
	v_or_b32_e32 v2, 11, v66
	v_cmp_gt_u32_e64 s[38:39], v2, v67
	v_or_b32_e32 v2, 43, v66
	v_cmp_gt_u32_e64 s[40:41], v2, v67
	v_or_b32_e32 v2, 16, v66
	v_cmp_gt_u32_e64 s[42:43], v2, v67
	v_or_b32_e32 v2, 48, v66
	v_cmp_gt_u32_e64 s[44:45], v2, v67
	v_or_b32_e32 v2, 17, v66
	v_cmp_gt_u32_e64 s[46:47], v2, v67
	v_or_b32_e32 v2, 49, v66
	v_cmp_gt_u32_e64 s[48:49], v2, v67
	v_or_b32_e32 v2, 18, v66
	v_cmp_gt_u32_e64 s[50:51], v2, v67
	v_or_b32_e32 v2, 50, v66
	v_cmp_gt_u32_e64 s[52:53], v2, v67
	v_or_b32_e32 v2, 19, v66
	v_cmp_gt_u32_e64 s[54:55], v2, v67
	v_or_b32_e32 v2, 51, v66
	v_cmp_gt_u32_e64 s[56:57], v2, v67
	v_or_b32_e32 v2, 24, v66
	v_cmp_gt_u32_e64 s[58:59], v2, v67
	v_or_b32_e32 v2, 56, v66
	v_cmp_gt_u32_e64 s[60:61], v2, v67
	v_or_b32_e32 v2, 25, v66
	v_cmp_gt_u32_e64 s[62:63], v2, v67
	v_or_b32_e32 v2, 57, v66
	v_cmp_gt_u32_e64 s[64:65], v2, v67
	v_or_b32_e32 v2, 26, v66
	v_cmp_gt_u32_e64 s[66:67], v2, v67
	v_or_b32_e32 v2, 58, v66
	v_cmp_gt_u32_e64 s[68:69], v2, v67
	v_or_b32_e32 v2, 27, v66
	v_cmp_gt_u32_e64 s[70:71], v2, v67
	v_or_b32_e32 v2, 59, v66
	v_lshlrev_b32_e32 v22, 16, v50
	v_and_b32_e32 v23, 0xffff0000, v50
	v_lshlrev_b32_e32 v24, 16, v51
	v_and_b32_e32 v25, 0xffff0000, v51
	s_add_i32 s1, 0, 0x1a800
	v_cmp_gt_u32_e64 s[8:9], v66, v67
	v_cmp_gt_u32_e64 s[72:73], v2, v67
	v_mov_b32_e32 v66, v5
	v_mov_b32_e32 v67, v5
	global_store_dwordx4 v[26:27], v[22:25], off
	s_bitcmp1_b32 s3, 7
	v_mov_b32_e32 v62, v5
	v_lshlrev_b32_e32 v22, 16, v52
	v_and_b32_e32 v23, 0xffff0000, v52
	v_lshlrev_b32_e32 v24, 16, v53
	v_and_b32_e32 v25, 0xffff0000, v53
	v_mov_b32_e32 v52, v5
	v_mov_b32_e32 v53, v5
	v_mov_b32_e32 v63, v5
	v_mov_b64_e32 v[82:83], v[66:67]
	v_lshl_add_u32 v186, v175, 3, s1
	s_cselect_b64 s[94:95], -1, 0
	s_mov_b32 s1, 0
	v_mov_b32_e32 v159, v5
	v_mov_b32_e32 v192, 0
	v_mov_b32_e32 v124, 0
	v_mov_b32_e32 v125, 0
	v_mov_b32_e32 v126, 0
	v_mov_b32_e32 v127, 0
	v_mov_b32_e32 v128, 0
	v_mov_b32_e32 v129, 0
	v_mov_b32_e32 v130, 0
	v_mov_b32_e32 v131, 0
	v_mov_b32_e32 v132, 0
	v_mov_b32_e32 v133, 0
	v_mov_b32_e32 v134, 0
	v_mov_b32_e32 v135, 0
	v_mov_b32_e32 v136, 0
	v_mov_b32_e32 v137, 0
	v_mov_b32_e32 v138, 0
	v_mov_b32_e32 v139, 0
	v_mov_b32_e32 v140, 0
	v_mov_b32_e32 v141, 0
	v_mov_b32_e32 v142, 0
	v_mov_b32_e32 v143, 0
	v_mov_b32_e32 v144, 0
	v_mov_b32_e32 v145, 0
	v_mov_b32_e32 v146, 0
	v_mov_b32_e32 v147, 0
	v_mov_b32_e32 v148, 0
	v_mov_b32_e32 v149, 0
	v_mov_b32_e32 v150, 0
	v_mov_b32_e32 v151, 0
	v_mov_b32_e32 v152, 0
	v_mov_b32_e32 v153, 0
	v_mov_b32_e32 v154, 0
	v_mov_b32_e32 v155, 0
	v_cndmask_b32_e64 v2, 0, v187, s[6:7]
	s_mov_b32 s75, 0
	v_mov_b64_e32 v[80:81], v[64:65]
	v_mov_b64_e32 v[78:79], v[62:63]
	v_mov_b64_e32 v[76:77], v[60:61]
	v_mov_b64_e32 v[74:75], v[58:59]
	v_mov_b64_e32 v[72:73], v[56:57]
	v_mov_b64_e32 v[70:71], v[54:55]
	v_mov_b64_e32 v[68:69], v[52:53]
	v_mov_b32_e32 v193, 0
	s_mov_b64 s[4:5], 0
	global_store_dwordx4 v[26:27], v[22:25], off offset:128
	s_waitcnt vmcnt(16) lgkmcnt(0)
	s_barrier
	v_mov_b64_e32 v[20:21], 0
	v_mov_b64_e32 v[22:23], 0
	v_mov_b64_e32 v[24:25], 0
	v_mov_b64_e32 v[26:27], 0
	v_mov_b64_e32 v[28:29], 0
	v_mov_b64_e32 v[30:31], 0
	v_mov_b64_e32 v[32:33], 0
	v_mov_b64_e32 v[34:35], 0
	v_mov_b64_e32 v[36:37], 0
	v_mov_b64_e32 v[38:39], 0
	v_mov_b64_e32 v[40:41], 0
	v_mov_b64_e32 v[42:43], 0
	v_mov_b64_e32 v[44:45], 0
	v_mov_b64_e32 v[46:47], 0
	v_mov_b64_e32 v[48:49], 0
	v_mov_b64_e32 v[50:51], 0
	s_branch .Lfox_top_l0

; #define LAS __attribute__((address_space(3)))
; #define ATT_WAIT_BAR() asm volatile("s_waitcnt vmcnt(0) lgkmcnt(0)\n\ts_barrier" ::: "memory")
; __device__ __forceinline__ void prompt_unit_fox(const Args& a, int l, int b, int h, int qb, LAS unsigned char* lds) {
;     ...
;         ATT_WAIT_BAR();
;         if (jp >= 1) ATT_DMA2(jp - 1, slot == 2 ? 0 : slot + 1);
;         const lds_cptr kslot = (lds_cptr)lds + F_K + slot * 16384; const lds_cptr vp = vp0 + slot * 16384;
;         const LAS float* ck0 = (const LAS float*)(lds + F_CK) + (2 * jp) * 64 + 4 * hi;
;         if (pending) { fox_pair_pv(st, pp, vp0 + pslot * 16384); pending = false; }
.Lfox_top_l0:
	s_cmp_lg_u32 s90, 0
	s_cbranch_scc0 .LBB0_343
	s_add_i32 s80, s90, -1
	s_mov_b32 s81, s87
	s_lshl_b32 s3, s75, 14
	s_lshl_b64 s[80:81], s[80:81], 18
	s_add_i32 s33, s3, 0x4000
	s_cmp_lg_u32 s75, 2
	s_cselect_b32 s33, s33, 0
	v_lshl_add_u64 v[244:245], v[176:177], 0, s[80:81]
	s_add_i32 s82, s79, s33
	s_mov_b32 s83, m0
	s_mov_b32 m0, s82
	s_nop 0
	global_load_lds_dwordx4 v[244:245], off
	s_mov_b32 m0, s83
	s_mov_b64 s[96:97], 0x20000
	v_lshl_add_u64 v[244:245], v[244:245], 0, s[96:97]
	s_add_i32 s82, s84, s33
	s_mov_b32 s83, m0
	s_mov_b32 m0, s82
	s_nop 0
	global_load_lds_dwordx4 v[244:245], off
	s_mov_b32 m0, s83
	v_lshl_add_u64 v[244:245], v[178:179], 0, s[80:81]
	s_add_i32 s80, s85, s33
	s_mov_b32 s81, m0
	s_mov_b32 m0, s80
	s_nop 0
	global_load_lds_dwordx4 v[244:245], off
	s_mov_b32 m0, s81
	v_lshl_add_u64 v[244:245], v[244:245], 0, s[96:97]
	s_add_i32 s33, s76, s33
	s_mov_b32 s80, m0
	s_mov_b32 m0, s33
	s_nop 0
	global_load_lds_dwordx4 v[244:245], off
	s_mov_b32 m0, s80
	s_cbranch_execnz .LBB0_315

; __device__ __forceinline__ void vfrags(VFrags& v, lds_cptr vp) {
; #pragma unroll
;     ...
; }
; __device__ __forceinline__ void pv(f32x16 (&o)[2], const VFrags& v, const u32x4& pw0, const u32x4& pw1, const u32x4& pw2, const u32x4& pw3) {
;     ...
;     o[0] = __builtin_amdgcn_mfma_f32_32x32x16_bf16(__builtin_bit_cast(bf16x8, pw0), ATT_VF(0), o[0], 0, 0, 0);
;     o[1] = __builtin_amdgcn_mfma_f32_32x32x16_bf16(__builtin_bit_cast(bf16x8, pw0), ATT_VF(4), o[1], 0, 0, 0);
;     o[0] = __builtin_amdgcn_mfma_f32_32x32x16_bf16(__builtin_bit_cast(bf16x8, pw1), ATT_VF(1), o[0], 0, 0, 0);
;     o[1] = __builtin_amdgcn_mfma_f32_32x32x16_bf16(__builtin_bit_cast(bf16x8, pw1), ATT_VF(5), o[1], 0, 0, 0);
;     o[0] = __builtin_amdgcn_mfma_f32_32x32x16_bf16(__builtin_bit_cast(bf16x8, pw2), ATT_VF(2), o[0], 0, 0, 0);
;     o[1] = __builtin_amdgcn_mfma_f32_32x32x16_bf16(__builtin_bit_cast(bf16x8, pw2), ATT_VF(6), o[1], 0, 0, 0);
;     o[0] = __builtin_amdgcn_mfma_f32_32x32x16_bf16(__builtin_bit_cast(bf16x8, pw3), ATT_VF(3), o[0], 0, 0, 0);
;     o[1] = __builtin_amdgcn_mfma_f32_32x32x16_bf16(__builtin_bit_cast(bf16x8, pw3), ATT_VF(7), o[1], 0, 0, 0);
;     ...
; }
; __device__ __forceinline__ void fox_pair_pv(FoxState& st, const PairP& pp, lds_cptr vpB) {
;     { VFrags vf; vfrags(vf, vpB + 8192); pv(st.o, vf, pp.w[0], pp.w[1], pp.w[2], pp.w[3]); }
;     { VFrags vf; vfrags(vf, vpB); pv(st.o, vf, pp.w[4], pp.w[5], pp.w[6], pp.w[7]); }
; }
.LBB0_315:
	s_andn2_b64 vcc, exec, s[4:5]
	s_cbranch_vccnz .LBB0_317
	v_lshl_add_u32 v3, s1, 14, v180
	ds_read_b64_tr_b16 v[84:85], v3 offset:57344
	ds_read_b64_tr_b16 v[86:87], v3 offset:57856
	ds_read_b64_tr_b16 v[88:89], v3 offset:61440
	ds_read_b64_tr_b16 v[90:91], v3 offset:61952
	ds_read_b64_tr_b16 v[92:93], v3 offset:58368
	ds_read_b64_tr_b16 v[94:95], v3 offset:58880
	ds_read_b64_tr_b16 v[96:97], v3 offset:62464
	ds_read_b64_tr_b16 v[98:99], v3 offset:62976
	ds_read_b64_tr_b16 v[100:101], v3 offset:59392
	ds_read_b64_tr_b16 v[102:103], v3 offset:59904
	ds_read_b64_tr_b16 v[104:105], v3 offset:63488
	ds_read_b64_tr_b16 v[106:107], v3 offset:64000
	ds_read_b64_tr_b16 v[108:109], v3 offset:60416
	ds_read_b64_tr_b16 v[110:111], v3 offset:60928
	s_waitcnt lgkmcnt(12)
	v_mfma_f32_32x32x16_bf16 v[20:35], v[152:155], v[84:87], v[20:35]
	ds_read_b64_tr_b16 v[112:113], v3 offset:64512
	ds_read_b64_tr_b16 v[114:115], v3 offset:65024
	s_waitcnt lgkmcnt(12)
	v_mfma_f32_32x32x16_bf16 v[36:51], v[152:155], v[88:91], v[36:51]
	ds_read_b64_tr_b16 v[84:85], v3 offset:49152
	ds_read_b64_tr_b16 v[86:87], v3 offset:49664
	s_waitcnt lgkmcnt(12)
	v_mfma_f32_32x32x16_bf16 v[20:35], v[148:151], v[92:95], v[20:35]
	ds_read_b64_tr_b16 v[88:89], v3 offset:53248
	ds_read_b64_tr_b16 v[90:91], v3 offset:53760
	s_waitcnt lgkmcnt(12)
	v_mfma_f32_32x32x16_bf16 v[36:51], v[148:151], v[96:99], v[36:51]
	ds_read_b64_tr_b16 v[92:93], v3 offset:50176
	ds_read_b64_tr_b16 v[94:95], v3 offset:50688
	s_waitcnt lgkmcnt(12)
	v_mfma_f32_32x32x16_bf16 v[20:35], v[144:147], v[100:103], v[20:35]
	ds_read_b64_tr_b16 v[96:97], v3 offset:54272
	ds_read_b64_tr_b16 v[98:99], v3 offset:54784
	s_waitcnt lgkmcnt(12)
	v_mfma_f32_32x32x16_bf16 v[36:51], v[144:147], v[104:107], v[36:51]
	ds_read_b64_tr_b16 v[100:101], v3 offset:51200
	ds_read_b64_tr_b16 v[102:103], v3 offset:51712
	s_waitcnt lgkmcnt(12)
	v_mfma_f32_32x32x16_bf16 v[20:35], v[140:143], v[108:111], v[20:35]
	ds_read_b64_tr_b16 v[104:105], v3 offset:55296
	ds_read_b64_tr_b16 v[106:107], v3 offset:55808
	s_waitcnt lgkmcnt(12)
	v_mfma_f32_32x32x16_bf16 v[36:51], v[140:143], v[112:115], v[36:51]
	ds_read_b64_tr_b16 v[108:109], v3 offset:52224
	ds_read_b64_tr_b16 v[110:111], v3 offset:52736
	s_waitcnt lgkmcnt(12)
	v_mfma_f32_32x32x16_bf16 v[20:35], v[136:139], v[84:87], v[20:35]
	ds_read_b64_tr_b16 v[112:113], v3 offset:56320
	ds_read_b64_tr_b16 v[114:115], v3 offset:56832
	s_waitcnt lgkmcnt(12)
	v_mfma_f32_32x32x16_bf16 v[36:51], v[136:139], v[88:91], v[36:51]
	s_waitcnt lgkmcnt(10)
	v_mfma_f32_32x32x16_bf16 v[20:35], v[132:135], v[92:95], v[20:35]
	s_waitcnt lgkmcnt(8)
	v_mfma_f32_32x32x16_bf16 v[36:51], v[132:135], v[96:99], v[36:51]
	s_waitcnt lgkmcnt(6)
	v_mfma_f32_32x32x16_bf16 v[20:35], v[128:131], v[100:103], v[20:35]
	s_waitcnt lgkmcnt(4)
	v_mfma_f32_32x32x16_bf16 v[36:51], v[128:131], v[104:107], v[36:51]
	s_waitcnt lgkmcnt(2)
	v_mfma_f32_32x32x16_bf16 v[20:35], v[124:127], v[108:111], v[20:35]
	s_waitcnt lgkmcnt(0)
	v_mfma_f32_32x32x16_bf16 v[36:51], v[124:127], v[112:115], v[36:51]
.LBB0_317:
	s_nop 9
	s_add_i32 s80, s3, 0
	s_lshl_b32 s81, s90, 7
	v_add_u32_e32 v190, s3, v180
	s_cmp_ge_i32 s90, s89
	s_mov_b64 s[4:5], -1
	s_cbranch_scc0 .LBB0_328
	v_mov_b64_e32 v[66:67], v[50:51]
	v_mov_b64_e32 v[82:83], v[34:35]
	v_mov_b64_e32 v[162:163], v[158:159]
	s_cmp_lg_u32 s90, s89
	v_mov_b64_e32 v[64:65], v[48:49]
	v_mov_b64_e32 v[62:63], v[46:47]
	v_mov_b64_e32 v[60:61], v[44:45]
	v_mov_b64_e32 v[58:59], v[42:43]
	v_mov_b64_e32 v[56:57], v[40:41]
	v_mov_b64_e32 v[54:55], v[38:39]
	v_mov_b64_e32 v[52:53], v[36:37]
	v_mov_b64_e32 v[80:81], v[32:33]
	v_mov_b64_e32 v[78:79], v[30:31]
	v_mov_b64_e32 v[76:77], v[28:29]
	v_mov_b64_e32 v[74:75], v[26:27]
	v_mov_b64_e32 v[72:73], v[24:25]
	v_mov_b64_e32 v[70:71], v[22:23]
	v_mov_b64_e32 v[68:69], v[20:21]
	v_mov_b64_e32 v[160:161], v[156:157]
	v_mov_b32_e32 v194, v192
	v_mov_b32_e32 v191, v193
	s_cbranch_scc1 .LBB0_327
	v_lshl_add_u32 v196, s81, 2, v184
	s_andn2_b64 vcc, exec, s[94:95]
	v_add3_u32 v195, s80, v173, v188
	s_cbranch_vccnz .LBB0_325
	ds_read_b128 v[68:71], v196 offset:256
	ds_read_b128 v[72:75], v196 offset:288
	ds_read_b128 v[76:79], v196 offset:320
	ds_read_b128 v[80:83], v196 offset:352
	ds_read_b128 v[52:55], v196 offset:384
	ds_read_b128 v[56:59], v196 offset:416
	ds_read_b128 v[60:63], v196 offset:448
	ds_read_b128 v[64:67], v196 offset:480
	ds_read_b128 v[84:87], v195 offset:8192
	s_waitcnt lgkmcnt(5)
	v_mfma_f32_32x32x16_bf16 v[68:83], v[120:123], v[156:159], v[68:83]
	s_waitcnt lgkmcnt(0)
	v_mfma_f32_32x32x16_bf16 v[68:83], v[84:87], v[6:9], v[68:83]
	ds_read_b128 v[84:87], v195 offset:8704
	v_mfma_f32_32x32x16_bf16 v[52:67], v[120:123], v[156:159], v[52:67]
	s_waitcnt lgkmcnt(0)
	v_mfma_f32_32x32x16_bf16 v[52:67], v[84:87], v[6:9], v[52:67]
	ds_read_b128 v[84:87], v195 offset:10240
	s_waitcnt lgkmcnt(0)
	v_mfma_f32_32x32x16_bf16 v[68:83], v[84:87], v[10:13], v[68:83]
	ds_read_b128 v[84:87], v195 offset:10752
	s_waitcnt lgkmcnt(0)
	v_mfma_f32_32x32x16_bf16 v[52:67], v[84:87], v[10:13], v[52:67]
	ds_read_b128 v[84:87], v195 offset:12288
	s_waitcnt lgkmcnt(0)
	v_mfma_f32_32x32x16_bf16 v[68:83], v[84:87], v[14:17], v[68:83]
	ds_read_b128 v[84:87], v195 offset:12800
	s_waitcnt lgkmcnt(0)
	v_mfma_f32_32x32x16_bf16 v[52:67], v[84:87], v[14:17], v[52:67]
	ds_read_b128 v[84:87], v195 offset:14336
	s_waitcnt lgkmcnt(0)
	v_mfma_f32_32x32x16_bf16 v[68:83], v[84:87], v[116:119], v[68:83]
	ds_read_b128 v[84:87], v195 offset:14848
	s_waitcnt lgkmcnt(0)
; #define LAS __attribute__((address_space(3)))
; __device__ __forceinline__ int crow(int r, int hi) { return (r & 3) + 8 * (r >> 2) + 4 * hi; }
; __device__ __forceinline__ float swap_max(float m) { auto rr = __builtin_amdgcn_permlane32_swap(__float_as_uint(m), __float_as_uint(m), false, false); return fmaxf(__uint_as_float(rr[0]), __uint_as_float(rr[1])); }
; __device__ __forceinline__ float max3f(float a, float b, float c) { return __builtin_fmaxf(__builtin_fmaxf(a, b), c); }
; __device__ __forceinline__ float fadd_s(float a, float b) { float r = a + b; asm volatile("" : "+v"(r)); return r; }
; #define ATT_LDS_WAIT() asm volatile("s_waitcnt lgkmcnt(0)" ::: "memory")
;     ...
;     if (masked) {
;         asm volatile("; masked tile" ::: "memory");
; #pragma unroll
;         for (int r = 0; r < 16; ++r) { const int kv = crow(r, hi); if (kv >= qlim) p0[r] = NEG; if (kv + 32 >= qlim) p1[r] = NEG; }
;     }
;     float rm = max3f(p0[0], p1[0], p0[1]), rm2 = max3f(p1[1], p0[2], p1[2]);
; #pragma unroll
;     for (int r = 3; r < 15; r += 2) { rm = max3f(rm, p0[r], p1[r]); rm2 = max3f(rm2, p0[r + 1], p1[r + 1]); }
;     rm = max3f(rm, p0[15], p1[15]); rm = swap_max(max3f(rm, rm2, rm2));
;     if (first || __any(rm > FOX_THR)) {
;         const float dl = first ? rm : fmaxf(rm, 0.f);
;         st.m += dl; st.mq = make_mq(st.m, hi);
; #pragma unroll
;         for (int r = 0; r < 16; ++r) { p0[r] -= dl; p1[r] -= dl; }
;         if (!first) {
;             const float f = __builtin_amdgcn_exp2f(-dl);
;             st.l *= f;
;             if (hi == 0) wsf[r32] = f;
;             ATT_LDS_WAIT();
; #pragma unroll
;             for (int g = 0; g < 4; ++g) { const f32x4 fv = *(const LAS f32x4*)(wsf + 8 * g + 4 * hi);
; #pragma unroll
;                 for (int i = 0; i < 4; ++i) { st.o[0][4 * g + i] *= fv[i]; st.o[1][4 * g + i] *= fv[i]; } }
;         }
;     }
;     __builtin_amdgcn_sched_barrier(0);
;     VFrags vf; vfrags(vf, vp);
;     float sacc = 0.f, sacc2 = 0.f;
; #pragma unroll
;     for (int r = 0; r < 16; ++r) { p0[r] = __builtin_amdgcn_exp2f(p0[r]); p1[r] = __builtin_amdgcn_exp2f(p1[r]); sacc = fadd_s(sacc, p0[r]); sacc2 = fadd_s(sacc2, p1[r]); }
	v_mfma_f32_32x32x16_bf16 v[52:67], v[84:87], v[116:119], v[52:67]
	s_and_b64 vcc, s[70:71], s[66:67]
	s_nop 7
	v_cndmask_b32_e32 v82, v82, v18, vcc
	s_and_b64 vcc, vcc, s[62:63]
	v_cndmask_b32_e32 v81, v81, v18, vcc
	s_and_b64 vcc, vcc, s[58:59]
	v_cndmask_b32_e32 v80, v80, v18, vcc
	s_and_b64 vcc, vcc, s[54:55]
	v_cndmask_b32_e32 v79, v79, v18, vcc
	s_and_b64 vcc, vcc, s[50:51]
	v_cndmask_b32_e32 v78, v78, v18, vcc
	s_and_b64 vcc, vcc, s[46:47]
	v_cndmask_b32_e32 v77, v77, v18, vcc
	s_and_b64 vcc, vcc, s[42:43]
	v_cndmask_b32_e32 v76, v76, v18, vcc
	s_and_b64 vcc, vcc, s[38:39]
	v_cndmask_b32_e32 v75, v75, v18, vcc
	s_and_b64 vcc, vcc, s[34:35]
	v_cndmask_b32_e32 v74, v74, v18, vcc
	s_and_b64 vcc, vcc, s[28:29]
	v_cndmask_b32_e32 v73, v73, v18, vcc
	s_and_b64 vcc, vcc, s[24:25]
	v_cndmask_b32_e64 v3, v68, v18, s[8:9]
	v_cndmask_b32_e32 v72, v72, v18, vcc
	s_and_b64 vcc, vcc, s[20:21]
	v_cndmask_b32_e64 v3, v3, v68, s[12:13]
	v_cndmask_b32_e64 v4, v18, v69, s[12:13]
	v_cndmask_b32_e32 v71, v71, v18, vcc
	s_and_b64 vcc, vcc, s[16:17]
	v_cndmask_b32_e32 v69, v69, v4, vcc
	v_cndmask_b32_e32 v68, v68, v3, vcc
	v_cndmask_b32_e32 v70, v70, v18, vcc
	s_and_b64 vcc, s[72:73], s[68:69]
	v_cndmask_b32_e32 v66, v66, v18, vcc
	s_and_b64 vcc, vcc, s[64:65]
	v_cndmask_b32_e32 v65, v65, v18, vcc
	s_and_b64 vcc, vcc, s[60:61]
	v_cndmask_b32_e32 v64, v64, v18, vcc
	s_and_b64 vcc, vcc, s[56:57]
	v_cndmask_b32_e32 v63, v63, v18, vcc
	s_and_b64 vcc, vcc, s[52:53]
	v_cndmask_b32_e32 v62, v62, v18, vcc
	s_and_b64 vcc, vcc, s[48:49]
	v_cndmask_b32_e32 v61, v61, v18, vcc
	s_and_b64 vcc, vcc, s[44:45]
	v_cndmask_b32_e32 v60, v60, v18, vcc
	s_and_b64 vcc, vcc, s[40:41]
	v_cndmask_b32_e32 v59, v59, v18, vcc
	s_and_b64 vcc, vcc, s[36:37]
	v_cndmask_b32_e32 v58, v58, v18, vcc
	s_and_b64 vcc, vcc, s[30:31]
	v_cndmask_b32_e32 v57, v57, v18, vcc
	s_and_b64 vcc, vcc, s[26:27]
	v_cndmask_b32_e32 v56, v56, v18, vcc
	s_and_b64 vcc, vcc, s[22:23]
	v_cndmask_b32_e32 v55, v55, v18, vcc
	s_and_b64 vcc, vcc, s[18:19]
	v_cndmask_b32_e32 v54, v54, v18, vcc
	s_and_b64 vcc, vcc, s[14:15]
	v_cndmask_b32_e32 v53, v53, v18, vcc
	s_and_b64 vcc, vcc, s[10:11]
	v_cndmask_b32_e32 v52, v52, v18, vcc
	v_max_f32_e32 v3, v68, v68
	v_max_f32_e32 v4, v52, v52
	v_max_f32_e32 v3, v3, v4
	v_max3_f32 v4, v53, v70, v54
	v_max3_f32 v3, v3, v69, v71
	v_max3_f32 v4, v4, v72, v56
	v_max3_f32 v3, v3, v55, v73
	v_max3_f32 v4, v4, v74, v58
	v_max3_f32 v3, v3, v57, v75
	v_max3_f32 v4, v4, v76, v60
	v_max3_f32 v3, v3, v59, v77
	v_max3_f32 v4, v4, v78, v62
	v_max3_f32 v3, v3, v61, v79
	v_cndmask_b32_e64 v83, v83, v18, s[70:71]
	v_max3_f32 v4, v4, v80, v64
	v_max3_f32 v3, v3, v63, v81
	v_cndmask_b32_e64 v67, v67, v18, s[72:73]
	v_max3_f32 v4, v4, v82, v66
	v_max3_f32 v3, v3, v65, v83
	v_max3_f32 v3, v3, v67, v4
	v_mov_b32_e32 v4, v3
	s_nop 1
	v_permlane32_swap_b32_e32 v3, v4
	v_max_f32_e32 v4, v4, v4
	v_max_f32_e32 v3, v3, v3
	v_max_f32_e32 v84, v3, v4
	v_add_f32_e32 v191, v193, v84
	v_cvt_pk_bf16_f32 v3, v191, 0
	v_lshlrev_b32_e32 v3, 16, v3
	v_sub_f32_e32 v4, v191, v3
	v_cvt_pk_bf16_f32 v85, v4, 0
	v_lshlrev_b32_e32 v85, 16, v85
	v_sub_f32_e32 v4, v4, v85
	v_cvt_pk_bf16_f32 v3, 1.0, v3
	v_cvt_pk_bf16_f32 v4, v85, v4
	v_cndmask_b32_e64 v4, 0, v4, s[6:7]
	v_cndmask_b32_e64 v3, 0, v3, s[6:7]
	v_sub_f32_e32 v68, v68, v84
	v_sub_f32_e32 v112, v52, v84
	v_sub_f32_e32 v69, v69, v84
	v_sub_f32_e32 v113, v53, v84
	v_sub_f32_e32 v70, v70, v84
	v_sub_f32_e32 v114, v54, v84
	v_sub_f32_e32 v71, v71, v84
	v_sub_f32_e32 v115, v55, v84
	v_sub_f32_e32 v72, v72, v84
	v_sub_f32_e32 v56, v56, v84
	v_sub_f32_e32 v73, v73, v84
	v_sub_f32_e32 v57, v57, v84
	v_sub_f32_e32 v74, v74, v84
	v_sub_f32_e32 v58, v58, v84
	v_sub_f32_e32 v75, v75, v84
	v_sub_f32_e32 v59, v59, v84
	v_sub_f32_e32 v76, v76, v84
	v_sub_f32_e32 v60, v60, v84
	v_sub_f32_e32 v77, v77, v84
	v_sub_f32_e32 v61, v61, v84
	v_sub_f32_e32 v78, v78, v84
	v_sub_f32_e32 v62, v62, v84
	v_sub_f32_e32 v79, v79, v84
	v_sub_f32_e32 v63, v63, v84
	v_sub_f32_e32 v80, v80, v84
	v_sub_f32_e32 v64, v64, v84
	v_sub_f32_e32 v81, v81, v84
	v_sub_f32_e32 v65, v65, v84
	v_sub_f32_e32 v82, v82, v84
	v_sub_f32_e32 v66, v66, v84
	v_sub_f32_e32 v83, v83, v84
	v_sub_f32_e32 v67, v67, v84
	v_exp_f32_e32 v68, v68
	v_exp_f32_e32 v164, v112
	v_exp_f32_e32 v69, v69
	v_exp_f32_e32 v165, v113
	v_add_f32_e32 v112, 0, v68
	v_exp_f32_e32 v70, v70
	ds_read_b64_tr_b16 v[52:53], v190 offset:57344
	ds_read_b64_tr_b16 v[54:55], v190 offset:57856
	ds_read_b64_tr_b16 v[84:85], v190 offset:58368
	ds_read_b64_tr_b16 v[86:87], v190 offset:58880
	ds_read_b64_tr_b16 v[88:89], v190 offset:59392
	ds_read_b64_tr_b16 v[90:91], v190 offset:59904
	ds_read_b64_tr_b16 v[92:93], v190 offset:60416
	ds_read_b64_tr_b16 v[94:95], v190 offset:60928
	ds_read_b64_tr_b16 v[96:97], v190 offset:61440
	ds_read_b64_tr_b16 v[98:99], v190 offset:61952
	ds_read_b64_tr_b16 v[100:101], v190 offset:62464
	ds_read_b64_tr_b16 v[102:103], v190 offset:62976
	ds_read_b64_tr_b16 v[104:105], v190 offset:63488
	ds_read_b64_tr_b16 v[106:107], v190 offset:64000
	ds_read_b64_tr_b16 v[108:109], v190 offset:64512
	ds_read_b64_tr_b16 v[110:111], v190 offset:65024
	v_exp_f32_e32 v166, v114
	v_add_f32_e32 v160, 0, v164
	v_add_f32_e32 v112, v112, v69
	v_exp_f32_e32 v71, v71
	v_exp_f32_e32 v167, v115
	v_add_f32_e32 v113, v160, v165
	v_add_f32_e32 v112, v112, v70
	v_exp_f32_e32 v72, v72
	v_add_f32_e32 v113, v113, v166
	v_exp_f32_e32 v56, v56
	v_add_f32_e32 v112, v112, v71
	v_exp_f32_e32 v73, v73
	v_add_f32_e32 v113, v113, v167
	v_exp_f32_e32 v57, v57
	v_add_f32_e32 v112, v112, v72
	v_exp_f32_e32 v74, v74
	v_add_f32_e32 v113, v113, v56
	v_exp_f32_e32 v58, v58
; __device__ __forceinline__ int crow(int r, int hi) { return (r & 3) + 8 * (r >> 2) + 4 * hi; }
; __device__ __forceinline__ unsigned cvtpk(float lo, float hi) { f32x2 v = {lo, hi}; bf16x2_t b = __builtin_convertvector(v, bf16x2_t); return __builtin_bit_cast(unsigned, b); }
; __device__ __forceinline__ float max3f(float a, float b, float c) { return __builtin_fmaxf(__builtin_fmaxf(a, b), c); }
;     bf16x8 kf[8]; kfrags(kf, kslot, r32, hi);
;     f32x16 p0, p1;
; #pragma unroll
;     for (int g = 0; g < 4; ++g) { const f32x4 c0 = ld4(ckt + 8 * g), c1 = ld4(ckt + 32 + 8 * g);
; #pragma unroll
;         for (int i = 0; i < 4; ++i) { p0[4 * g + i] = c0[i]; p1[4 * g + i] = c1[i]; } }
;     u32x4 kn = {0u, 0xBF800000u, 0xBF80BF80u, 0u}; if (hi) { kn.y = 0u; kn.z = 0u; }
;     const bf16x8 kneg = __builtin_bit_cast(bf16x8, kn);
;     p0 = __builtin_amdgcn_mfma_f32_32x32x16_bf16(kneg, st.mq, p0, 0, 0, 0);
;     p1 = __builtin_amdgcn_mfma_f32_32x32x16_bf16(kneg, st.mq, p1, 0, 0, 0);
; #pragma unroll
;     for (int d0 = 0; d0 < 4; ++d0) {
;         p0 = __builtin_amdgcn_mfma_f32_32x32x16_bf16(kf[2 * d0], qr[d0], p0, 0, 0, 0);
;         p1 = __builtin_amdgcn_mfma_f32_32x32x16_bf16(kf[2 * d0 + 1], qr[d0], p1, 0, 0, 0);
;     }
;     __builtin_amdgcn_sched_barrier(0);
;     if (LEVEL == 2) { asm volatile("" :: "v"(p0), "v"(p1)); return; }
;     if (masked) {
;         asm volatile("; masked tile" ::: "memory");
; #pragma unroll
;         for (int r = 0; r < 16; ++r) { const int kv = crow(r, hi); if (kv >= qlim) p0[r] = NEG; if (kv + 32 >= qlim) p1[r] = NEG; }
;     }
;     float rm = max3f(p0[0], p1[0], p0[1]), rm2 = max3f(p1[1], p0[2], p1[2]);
; #pragma unroll
;     for (int r = 3; r < 15; r += 2) { rm = max3f(rm, p0[r], p1[r]); rm2 = max3f(rm2, p0[r + 1], p1[r + 1]); }
;     rm = max3f(rm, p0[15], p1[15]); rm = swap_max(max3f(rm, rm2, rm2));
;     ...
;     for (int r = 0; r < 16; ++r) { p0[r] = __builtin_amdgcn_exp2f(p0[r]); p1[r] = __builtin_amdgcn_exp2f(p1[r]); sacc = fadd_s(sacc, p0[r]); sacc2 = fadd_s(sacc2, p1[r]); }
;     st.l = fadd_s(st.l, fadd_s(sacc, sacc2));
;     const u32x4 pw0 = ATT_PACK4(p0, 0, cvtpk), pw1 = ATT_PACK4(p0, 8, cvtpk), pw2 = ATT_PACK4(p1, 0, cvtpk), pw3 = ATT_PACK4(p1, 8, cvtpk);
;     __builtin_amdgcn_sched_barrier(0);
;     ...
;     pv(st.o, vf, pw0, pw1, pw2, pw3);
	v_add_f32_e32 v112, v112, v73
	v_exp_f32_e32 v75, v75
	v_add_f32_e32 v113, v113, v57
	v_exp_f32_e32 v59, v59
	v_add_f32_e32 v112, v112, v74
	v_exp_f32_e32 v76, v76
	v_add_f32_e32 v113, v113, v58
	v_exp_f32_e32 v60, v60
	v_add_f32_e32 v112, v112, v75
	v_exp_f32_e32 v77, v77
	v_add_f32_e32 v113, v113, v59
	v_exp_f32_e32 v61, v61
	v_add_f32_e32 v112, v76, v112
	v_exp_f32_e32 v78, v78
	v_add_f32_e32 v113, v60, v113
	v_exp_f32_e32 v62, v62
	v_add_f32_e32 v112, v77, v112
	v_exp_f32_e32 v79, v79
	v_add_f32_e32 v113, v61, v113
	v_exp_f32_e32 v63, v63
	v_add_f32_e32 v112, v78, v112
	v_exp_f32_e32 v80, v80
	v_add_f32_e32 v113, v62, v113
	v_exp_f32_e32 v64, v64
	v_add_f32_e32 v112, v79, v112
	v_exp_f32_e32 v81, v81
	v_add_f32_e32 v113, v63, v113
	v_exp_f32_e32 v65, v65
	v_add_f32_e32 v112, v80, v112
	v_exp_f32_e32 v82, v82
	v_add_f32_e32 v113, v64, v113
	v_exp_f32_e32 v66, v66
	v_add_f32_e32 v112, v81, v112
	v_exp_f32_e32 v83, v83
	v_add_f32_e32 v113, v65, v113
	v_exp_f32_e32 v67, v67
	v_add_f32_e32 v112, v82, v112
	v_add_f32_e32 v113, v66, v113
	v_add_f32_e32 v112, v83, v112
	v_add_f32_e32 v113, v67, v113
	v_cvt_pk_bf16_f32 v114, v72, v73
	v_add_f32_e32 v112, v112, v113
	v_cvt_pk_bf16_f32 v113, v70, v71
	v_add_f32_e32 v194, v192, v112
	v_cvt_pk_bf16_f32 v112, v68, v69
	v_cvt_pk_bf16_f32 v115, v74, v75
	v_cvt_pk_bf16_f32 v160, v76, v77
	v_cvt_pk_bf16_f32 v161, v78, v79
	v_cvt_pk_bf16_f32 v162, v80, v81
	v_cvt_pk_bf16_f32 v163, v82, v83
	v_cvt_pk_bf16_f32 v164, v164, v165
	v_cvt_pk_bf16_f32 v165, v166, v167
	v_cvt_pk_bf16_f32 v166, v56, v57
	v_cvt_pk_bf16_f32 v167, v58, v59
	v_cvt_pk_bf16_f32 v198, v60, v61
	v_cvt_pk_bf16_f32 v199, v62, v63
	v_cvt_pk_bf16_f32 v200, v64, v65
	v_cvt_pk_bf16_f32 v201, v66, v67
	s_waitcnt lgkmcnt(14)
	v_mfma_f32_32x32x16_bf16 v[68:83], v[112:115], v[52:55], v[20:35]
	s_waitcnt lgkmcnt(6)
	v_mfma_f32_32x32x16_bf16 v[52:67], v[112:115], v[96:99], v[36:51]
	v_mfma_f32_32x32x16_bf16 v[68:83], v[160:163], v[84:87], v[68:83]
	s_waitcnt lgkmcnt(4)
	v_mfma_f32_32x32x16_bf16 v[52:67], v[160:163], v[100:103], v[52:67]
	v_mfma_f32_32x32x16_bf16 v[68:83], v[164:167], v[88:91], v[68:83]
	s_waitcnt lgkmcnt(2)
	v_mfma_f32_32x32x16_bf16 v[52:67], v[164:167], v[104:107], v[52:67]
	v_mfma_f32_32x32x16_bf16 v[68:83], v[198:201], v[92:95], v[68:83]
	ds_read_b128 v[84:87], v196
	ds_read_b128 v[88:91], v196 offset:32
	ds_read_b128 v[92:95], v196 offset:64
	ds_read_b128 v[96:99], v196 offset:96
	s_waitcnt lgkmcnt(4)
	v_mfma_f32_32x32x16_bf16 v[52:67], v[198:201], v[108:111], v[52:67]
	ds_read_b128 v[100:103], v196 offset:128
	ds_read_b128 v[104:107], v196 offset:160
	ds_read_b128 v[108:111], v196 offset:192
	ds_read_b128 v[112:115], v196 offset:224
	ds_read_b128 v[160:163], v195
	ds_read_b128 v[164:167], v195 offset:512
	s_waitcnt lgkmcnt(6)
	v_mfma_f32_32x32x16_bf16 v[84:99], v[120:123], v[2:5], v[84:99]
	s_waitcnt lgkmcnt(2)
	v_mfma_f32_32x32x16_bf16 v[100:115], v[120:123], v[2:5], v[100:115]
	s_waitcnt lgkmcnt(1)
	v_mfma_f32_32x32x16_bf16 v[84:99], v[160:163], v[6:9], v[84:99]
	s_waitcnt lgkmcnt(0)
	v_mfma_f32_32x32x16_bf16 v[100:115], v[164:167], v[6:9], v[100:115]
	ds_read_b128 v[160:163], v195 offset:2048
	ds_read_b128 v[164:167], v195 offset:2560
	s_waitcnt lgkmcnt(1)
	v_mfma_f32_32x32x16_bf16 v[84:99], v[160:163], v[10:13], v[84:99]
	s_waitcnt lgkmcnt(0)
	v_mfma_f32_32x32x16_bf16 v[100:115], v[164:167], v[10:13], v[100:115]
	ds_read_b128 v[160:163], v195 offset:4096
	ds_read_b128 v[164:167], v195 offset:4608
	s_waitcnt lgkmcnt(1)
	v_mfma_f32_32x32x16_bf16 v[84:99], v[160:163], v[14:17], v[84:99]
	s_waitcnt lgkmcnt(0)
	v_mfma_f32_32x32x16_bf16 v[100:115], v[164:167], v[14:17], v[100:115]
	ds_read_b128 v[160:163], v195 offset:6144
	ds_read_b128 v[164:167], v195 offset:6656
	s_waitcnt lgkmcnt(1)
	v_mfma_f32_32x32x16_bf16 v[84:99], v[160:163], v[116:119], v[84:99]
	s_waitcnt lgkmcnt(0)
	v_mfma_f32_32x32x16_bf16 v[100:115], v[164:167], v[116:119], v[100:115]
	s_nop 11
	v_max_f32_e32 v160, v100, v100
	v_max_f32_e32 v161, v84, v84
	v_max_f32_e32 v160, v161, v160
	v_max3_f32 v161, v101, v86, v102
	v_max3_f32 v160, v160, v85, v87
	v_max3_f32 v161, v161, v88, v104
	v_max3_f32 v160, v160, v103, v89
	v_max3_f32 v161, v161, v90, v106
	v_max3_f32 v160, v160, v105, v91
	v_max3_f32 v161, v161, v92, v108
	v_max3_f32 v160, v160, v107, v93
	v_max3_f32 v161, v161, v94, v110
	v_max3_f32 v160, v160, v109, v95
	v_max3_f32 v161, v161, v96, v112
	v_max3_f32 v160, v160, v111, v97
	v_max3_f32 v161, v161, v98, v114
	v_max3_f32 v160, v160, v113, v99
	v_max3_f32 v160, v160, v115, v161
	v_mov_b32_e32 v161, v160
	s_nop 1
	v_permlane32_swap_b32_e32 v160, v161
	v_max_f32_e32 v161, v161, v161
	v_max_f32_e32 v160, v160, v160
	v_max_f32_e32 v160, v160, v161
	s_mov_b32 s3, 0x41000000
	v_cmp_lt_f32_e32 vcc, s3, v160
	s_cbranch_vccz .LBB0_324
; #define LAS __attribute__((address_space(3)))
; #define ATT_LDS_WAIT() asm volatile("s_waitcnt lgkmcnt(0)" ::: "memory")
;     ...
;     if (first || __any(rm > FOX_THR)) {
;         const float dl = first ? rm : fmaxf(rm, 0.f);
;         st.m += dl; st.mq = make_mq(st.m, hi);
; #pragma unroll
;         for (int r = 0; r < 16; ++r) { p0[r] -= dl; p1[r] -= dl; }
;         if (!first) {
;             const float f = __builtin_amdgcn_exp2f(-dl);
;             st.l *= f;
;             if (hi == 0) wsf[r32] = f;
;             ATT_LDS_WAIT();
; #pragma unroll
;             for (int g = 0; g < 4; ++g) { const f32x4 fv = *(const LAS f32x4*)(wsf + 8 * g + 4 * hi);
; #pragma unroll
;                 for (int i = 0; i < 4; ++i) { st.o[0][4 * g + i] *= fv[i]; st.o[1][4 * g + i] *= fv[i]; } }
;         }
;     }
	v_max_f32_e32 v3, v160, v160
	v_max_f32_e32 v160, 0, v3
	v_exp_f32_e64 v161, -v160
	s_and_saveexec_b64 s[4:5], s[6:7]
	ds_write_b32 v182, v161
	s_or_b64 exec, exec, s[4:5]
	v_add_f32_e32 v191, v191, v160
	v_cvt_pk_bf16_f32 v3, v191, 0
	v_lshlrev_b32_e32 v3, 16, v3
	v_sub_f32_e32 v4, v191, v3
	v_cvt_pk_bf16_f32 v162, v4, 0
	v_lshlrev_b32_e32 v162, 16, v162
	v_sub_f32_e32 v4, v4, v162
	s_waitcnt lgkmcnt(0)
	v_add_u32_e32 v197, s78, v172
	v_cvt_pk_bf16_f32 v4, v162, v4
	v_pk_add_f32 v[84:85], v[84:85], v[160:161] op_sel_hi:[1,0] neg_lo:[0,1] neg_hi:[0,1]
	v_pk_add_f32 v[100:101], v[100:101], v[160:161] op_sel_hi:[1,0] neg_lo:[0,1] neg_hi:[0,1]
	v_pk_add_f32 v[86:87], v[86:87], v[160:161] op_sel_hi:[1,0] neg_lo:[0,1] neg_hi:[0,1]
	v_pk_add_f32 v[102:103], v[102:103], v[160:161] op_sel_hi:[1,0] neg_lo:[0,1] neg_hi:[0,1]
	v_pk_add_f32 v[88:89], v[88:89], v[160:161] op_sel_hi:[1,0] neg_lo:[0,1] neg_hi:[0,1]
	v_pk_add_f32 v[104:105], v[104:105], v[160:161] op_sel_hi:[1,0] neg_lo:[0,1] neg_hi:[0,1]
	v_pk_add_f32 v[90:91], v[90:91], v[160:161] op_sel_hi:[1,0] neg_lo:[0,1] neg_hi:[0,1]
	v_pk_add_f32 v[106:107], v[106:107], v[160:161] op_sel_hi:[1,0] neg_lo:[0,1] neg_hi:[0,1]
	v_pk_add_f32 v[92:93], v[92:93], v[160:161] op_sel_hi:[1,0] neg_lo:[0,1] neg_hi:[0,1]
	v_pk_add_f32 v[108:109], v[108:109], v[160:161] op_sel_hi:[1,0] neg_lo:[0,1] neg_hi:[0,1]
	v_pk_add_f32 v[94:95], v[94:95], v[160:161] op_sel_hi:[1,0] neg_lo:[0,1] neg_hi:[0,1]
	v_pk_add_f32 v[110:111], v[110:111], v[160:161] op_sel_hi:[1,0] neg_lo:[0,1] neg_hi:[0,1]
	v_pk_add_f32 v[96:97], v[96:97], v[160:161] op_sel_hi:[1,0] neg_lo:[0,1] neg_hi:[0,1]
	v_pk_add_f32 v[112:113], v[112:113], v[160:161] op_sel_hi:[1,0] neg_lo:[0,1] neg_hi:[0,1]
	v_pk_add_f32 v[98:99], v[98:99], v[160:161] op_sel_hi:[1,0] neg_lo:[0,1] neg_hi:[0,1]
	v_pk_add_f32 v[114:115], v[114:115], v[160:161] op_sel_hi:[1,0] neg_lo:[0,1] neg_hi:[0,1]
	v_mul_f32_e32 v194, v194, v161
	ds_read_b128 v[160:163], v197
	ds_read_b128 v[164:167], v197 offset:32
	ds_read_b128 v[198:201], v197 offset:64
	ds_read_b128 v[202:205], v197 offset:96
	v_cvt_pk_bf16_f32 v3, 1.0, v3
	v_cndmask_b32_e64 v4, 0, v4, s[6:7]
	v_cndmask_b32_e64 v3, 0, v3, s[6:7]
	s_waitcnt lgkmcnt(1)
	v_pk_mul_f32 v[76:77], v[76:77], v[198:199]
	s_waitcnt lgkmcnt(0)
	v_pk_mul_f32 v[80:81], v[80:81], v[202:203]
	v_pk_mul_f32 v[72:73], v[72:73], v[164:165]
	v_pk_mul_f32 v[82:83], v[82:83], v[204:205]
	v_pk_mul_f32 v[78:79], v[78:79], v[200:201]
	v_pk_mul_f32 v[74:75], v[74:75], v[166:167]
	v_pk_mul_f32 v[70:71], v[70:71], v[162:163]
	v_pk_mul_f32 v[68:69], v[68:69], v[160:161]
	v_pk_mul_f32 v[64:65], v[64:65], v[202:203]
	v_pk_mul_f32 v[60:61], v[60:61], v[198:199]
	v_pk_mul_f32 v[56:57], v[56:57], v[164:165]
	v_pk_mul_f32 v[66:67], v[66:67], v[204:205]
	v_pk_mul_f32 v[62:63], v[62:63], v[200:201]
	v_pk_mul_f32 v[58:59], v[58:59], v[166:167]
	v_pk_mul_f32 v[54:55], v[54:55], v[162:163]
	v_pk_mul_f32 v[52:53], v[52:53], v[160:161]

; __device__ __forceinline__ void prompt_unit_fox(const Args& a, int l, int b, int h, int qb, LAS unsigned char* lds) {
;     ...
;             if (lateB) { pending = true; pslot = slot; } else fox_pair_pv(st, pp, vp);
;         } else if (jp == jpd) {
;             if (jd & 1) { fox_tile(st, kslot + 8192, vp + 8192, qr, ck0 + 64, true, true, qlim, r32, hi, wsf); fox_tile(st, kslot, vp, qr, ck0, false, false, qlim, r32, hi, wsf); }
;             else fox_tile(st, kslot, vp, qr, ck0, true, true, qlim, r32, hi, wsf);
;         }
;         slot = (slot == 2) ? 0 : slot + 1;
.LBB0_340:
	s_mov_b64 s[4:5], 0
	s_nop 15
	v_mov_b64_e32 v[20:21], v[68:69]
	v_mov_b64_e32 v[22:23], v[70:71]
	v_mov_b64_e32 v[24:25], v[72:73]
	v_mov_b64_e32 v[26:27], v[74:75]
	v_mov_b64_e32 v[28:29], v[76:77]
	v_mov_b64_e32 v[30:31], v[78:79]
	v_mov_b64_e32 v[32:33], v[80:81]
	v_mov_b64_e32 v[34:35], v[82:83]
	v_mov_b64_e32 v[36:37], v[52:53]
	v_mov_b64_e32 v[38:39], v[54:55]
	v_mov_b64_e32 v[40:41], v[56:57]
	v_mov_b64_e32 v[42:43], v[58:59]
	v_mov_b64_e32 v[44:45], v[60:61]
	v_mov_b64_e32 v[46:47], v[62:63]
	v_mov_b64_e32 v[48:49], v[64:65]
	v_mov_b64_e32 v[50:51], v[66:67]
	s_branch .LBB0_346

; __device__ __forceinline__ void vfrags(VFrags& v, lds_cptr vp) {
; #pragma unroll
;     ...
; }
; __device__ __forceinline__ void pv(f32x16 (&o)[2], const VFrags& v, const u32x4& pw0, const u32x4& pw1, const u32x4& pw2, const u32x4& pw3) {
;     ...
;     o[0] = __builtin_amdgcn_mfma_f32_32x32x16_bf16(__builtin_bit_cast(bf16x8, pw0), ATT_VF(0), o[0], 0, 0, 0);
;     o[1] = __builtin_amdgcn_mfma_f32_32x32x16_bf16(__builtin_bit_cast(bf16x8, pw0), ATT_VF(4), o[1], 0, 0, 0);
;     o[0] = __builtin_amdgcn_mfma_f32_32x32x16_bf16(__builtin_bit_cast(bf16x8, pw1), ATT_VF(1), o[0], 0, 0, 0);
;     o[1] = __builtin_amdgcn_mfma_f32_32x32x16_bf16(__builtin_bit_cast(bf16x8, pw1), ATT_VF(5), o[1], 0, 0, 0);
;     o[0] = __builtin_amdgcn_mfma_f32_32x32x16_bf16(__builtin_bit_cast(bf16x8, pw2), ATT_VF(2), o[0], 0, 0, 0);
;     o[1] = __builtin_amdgcn_mfma_f32_32x32x16_bf16(__builtin_bit_cast(bf16x8, pw2), ATT_VF(6), o[1], 0, 0, 0);
;     o[0] = __builtin_amdgcn_mfma_f32_32x32x16_bf16(__builtin_bit_cast(bf16x8, pw3), ATT_VF(3), o[0], 0, 0, 0);
;     o[1] = __builtin_amdgcn_mfma_f32_32x32x16_bf16(__builtin_bit_cast(bf16x8, pw3), ATT_VF(7), o[1], 0, 0, 0);
;     ...
; }
; __device__ __forceinline__ void prompt_unit_fox(const Args& a, int l, int b, int h, int qb, LAS unsigned char* lds) {
;     ...
;         slot = (slot == 2) ? 0 : slot + 1;
;     }
;     ...
;     if (pending) fox_pair_pv(st, pp, vp0 + pslot * 16384);
.LBB0_345:
	s_nop 10
.LBB0_346:
	s_add_i32 s3, s75, 1
	s_cmp_lg_u32 s75, 2
	s_cselect_b32 s75, s3, 0
	s_add_i32 s3, s90, -1
	s_cmp_lt_i32 s90, 1
	s_cbranch_scc1 .LBB0_348
	v_mov_b64_e32 v[156:157], v[160:161]
	s_mov_b32 s90, s3
	v_mov_b64_e32 v[158:159], v[162:163]
	v_mov_b32_e32 v192, v194
	v_mov_b32_e32 v193, v191
	s_branch .LBB0_312
.LBB0_348:
	s_nop 3
	v_mov_b64_e32 v[68:69], v[20:21]
	v_mov_b64_e32 v[70:71], v[22:23]
	v_mov_b64_e32 v[72:73], v[24:25]
	v_mov_b64_e32 v[74:75], v[26:27]
	v_mov_b64_e32 v[76:77], v[28:29]
	v_mov_b64_e32 v[78:79], v[30:31]
	v_mov_b64_e32 v[80:81], v[32:33]
	v_mov_b64_e32 v[82:83], v[34:35]
	v_mov_b64_e32 v[52:53], v[36:37]
	v_mov_b64_e32 v[54:55], v[38:39]
	v_mov_b64_e32 v[56:57], v[40:41]
	v_mov_b64_e32 v[58:59], v[42:43]
	v_mov_b64_e32 v[60:61], v[44:45]
	v_mov_b64_e32 v[62:63], v[46:47]
	v_mov_b64_e32 v[64:65], v[48:49]
	v_mov_b64_e32 v[66:67], v[50:51]
	s_and_b64 vcc, exec, s[4:5]
	s_cbranch_vccz .LBB0_350
	v_lshl_add_u32 v2, s1, 14, v180
	ds_read_b64_tr_b16 v[6:7], v2 offset:57344
	ds_read_b64_tr_b16 v[8:9], v2 offset:57856
	ds_read_b64_tr_b16 v[10:11], v2 offset:58368
	ds_read_b64_tr_b16 v[12:13], v2 offset:58880
	s_waitcnt lgkmcnt(2)
	v_mfma_f32_32x32x16_bf16 v[68:83], v[152:155], v[6:9], v[68:83]
	ds_read_b64_tr_b16 v[6:7], v2 offset:61440
	ds_read_b64_tr_b16 v[8:9], v2 offset:61952
	ds_read_b64_tr_b16 v[14:15], v2 offset:62464
	ds_read_b64_tr_b16 v[16:17], v2 offset:62976
	s_waitcnt lgkmcnt(2)
	v_mfma_f32_32x32x16_bf16 v[52:67], v[152:155], v[6:9], v[52:67]
	v_mfma_f32_32x32x16_bf16 v[68:83], v[148:151], v[10:13], v[68:83]
	ds_read_b64_tr_b16 v[6:7], v2 offset:59392
	ds_read_b64_tr_b16 v[8:9], v2 offset:59904
	ds_read_b64_tr_b16 v[10:11], v2 offset:60416
	ds_read_b64_tr_b16 v[12:13], v2 offset:60928
	s_waitcnt lgkmcnt(4)
	v_mfma_f32_32x32x16_bf16 v[52:67], v[148:151], v[14:17], v[52:67]
	s_waitcnt lgkmcnt(2)
	v_mfma_f32_32x32x16_bf16 v[68:83], v[144:147], v[6:9], v[68:83]
	ds_read_b64_tr_b16 v[6:7], v2 offset:63488
	ds_read_b64_tr_b16 v[8:9], v2 offset:64000
	ds_read_b64_tr_b16 v[14:15], v2 offset:64512
	ds_read_b64_tr_b16 v[16:17], v2 offset:65024
	s_waitcnt lgkmcnt(2)
	v_mfma_f32_32x32x16_bf16 v[52:67], v[144:147], v[6:9], v[52:67]
	v_mfma_f32_32x32x16_bf16 v[68:83], v[140:143], v[10:13], v[68:83]
	ds_read_b64_tr_b16 v[6:7], v2 offset:49152
	ds_read_b64_tr_b16 v[8:9], v2 offset:49664
	ds_read_b64_tr_b16 v[10:11], v2 offset:50176
	ds_read_b64_tr_b16 v[12:13], v2 offset:50688
	s_waitcnt lgkmcnt(4)
	v_mfma_f32_32x32x16_bf16 v[52:67], v[140:143], v[14:17], v[52:67]
	s_waitcnt lgkmcnt(2)
	v_mfma_f32_32x32x16_bf16 v[68:83], v[136:139], v[6:9], v[68:83]
	ds_read_b64_tr_b16 v[6:7], v2 offset:53248
	ds_read_b64_tr_b16 v[8:9], v2 offset:53760
	ds_read_b64_tr_b16 v[14:15], v2 offset:54272
	ds_read_b64_tr_b16 v[16:17], v2 offset:54784
	s_waitcnt lgkmcnt(2)
	v_mfma_f32_32x32x16_bf16 v[52:67], v[136:139], v[6:9], v[52:67]
	v_mfma_f32_32x32x16_bf16 v[68:83], v[132:135], v[10:13], v[68:83]
	ds_read_b64_tr_b16 v[6:7], v2 offset:51200
	ds_read_b64_tr_b16 v[8:9], v2 offset:51712
	ds_read_b64_tr_b16 v[10:11], v2 offset:52224
	ds_read_b64_tr_b16 v[12:13], v2 offset:52736
	s_waitcnt lgkmcnt(4)
	v_mfma_f32_32x32x16_bf16 v[52:67], v[132:135], v[14:17], v[52:67]
	s_waitcnt lgkmcnt(2)
	v_mfma_f32_32x32x16_bf16 v[68:83], v[128:131], v[6:9], v[68:83]
	ds_read_b64_tr_b16 v[6:7], v2 offset:55296
	ds_read_b64_tr_b16 v[8:9], v2 offset:55808
	ds_read_b64_tr_b16 v[14:15], v2 offset:56320
	ds_read_b64_tr_b16 v[16:17], v2 offset:56832
	s_waitcnt lgkmcnt(2)
	v_mfma_f32_32x32x16_bf16 v[52:67], v[128:131], v[6:9], v[52:67]
	v_mfma_f32_32x32x16_bf16 v[68:83], v[124:127], v[10:13], v[68:83]
	s_waitcnt lgkmcnt(0)
	v_mfma_f32_32x32x16_bf16 v[52:67], v[124:127], v[14:17], v[52:67]

; #define LAS __attribute__((address_space(3)))
; __device__ __forceinline__ unsigned cvtpk(float lo, float hi) { f32x2 v = {lo, hi}; bf16x2_t b = __builtin_convertvector(v, bf16x2_t); return __builtin_bit_cast(unsigned, b); }
; __device__ __forceinline__ void prompt_unit_fox(const Args& a, int l, int b, int h, int qb, LAS unsigned char* lds) {
;     int tid_ = threadIdx.x; asm volatile("" : "+v"(tid_));
;     const int tid = tid_, lane = tid & 63, r32 = lane & 31, hi = lane >> 5, wid = __builtin_amdgcn_readfirstlane(tid >> 6);
;     const int q0 = qb * 256, NP = (q0 + 256) / 128, jd = q0 / 64 + (wid >> 1), jpd = jd >> 1;
;     const bool lateB = wid >= 4;
;     const int col = h * HD;
;     const size_t rowb = (size_t)b * T;
;     const bf16* Kh = (const bf16*)(a.ws + WS_K) + rowb * D + col; const bf16* Vh = (const bf16*)(a.ws + WS_V) + rowb * D + col;
;     const unsigned lds0 = (unsigned)(uintptr_t)lds;
;     const bf16* ksrc = Kh + (size_t)lane * D + wid * 8;
;     const bf16* vsrc = Vh + (size_t)(16 * (wid & 3) + (lane >> 2)) * D + (wid >> 2) * 32 + (lane & 3) * 8;
;     ...
;     ATT_DMA2(NP - 1, 0);
;     { const int idx = tid * 4; if (idx < q0 + 256) { const f32x4 c = *(const f32x4*)((const float*)(a.ws + WS_CKP) + (size_t)(b * 8 + h) * T + idx); *(LAS f32x4*)(lds + F_CK + idx * 4) = c;
; #pragma unroll
;         for (int e = 0; e < 4; ++e) { const float h1 = bf_hi_part(c[e]), r1 = c[e] - h1, h2 = bf_hi_part(r1), r2 = r1 - h2; ((LAS u32x2*)(lds + F_AUG))[idx + e] = (u32x2){cvtpk(h1, h2), cvtpk(r2, -1.0f)}; } } }
;     bf16x8 qr[4];
;     { const bf16* Qw = (const bf16*)(a.ws + WS_Q) + (rowb + q0 + wid * 32 + r32) * D + col;
; #pragma unroll
;       for (int d0 = 0; d0 < 4; ++d0) qr[d0] = *(const bf16x8*)(Qw + d0 * 16 + hi * 8); }
;     const lds_cptr vp0 = (lds_cptr)lds + F_V + ((lane >> 4) & 1) * 32 + (lane & 3) * 8 + (4 * hi + ((lane & 15) >> 2)) * 64;
;     const int ql = 32 * (wid & 1) + r32, qlim = ql + 1;
;     LAS float* wsf = (LAS float*)(lds + F_WSF) + wid * 64;
;     FoxState st; st.m = 0.f; st.l = 0.f; st.mq = (bf16x8){}; st.o[0] = (f32x16){}; st.o[1] = (f32x16){};
;     PairP pp; bool pending = false;
; #pragma unroll
;     for (int i = 0; i < 8; ++i) pp.w[i] = (u32x4){0u, 0u, 0u, 0u};
;     { ConvRegs cv; conv_load(cv, a, rowb + q0 + wid * 32, col, lane); conv_store<0>(cv, a, l, h, rowb + q0 + wid * 32, lane); }
.LBB0_963:
	v_writelane_b32 v242, s16, 32
	s_or_b64 exec, exec, s[2:3]
	s_lshl_b32 s0, s0, 2
	s_ashr_i32 s2, s6, 7
	s_add_i32 s2, s2, s0
	s_ashr_i32 s0, s2, 1
	s_cmp_lt_i32 s1, 4
	s_cselect_b64 s[90:91], -1, 0
	s_lshl_b32 s2, s8, 11
	s_lshl_b32 s3, s1, 5
	s_or_b32 s2, s9, s2
	s_ashr_i32 s8, s3, 31
	s_add_u32 s79, s3, s2
	v_and_b32_e32 v180, 31, v19
	s_addc_u32 s10, s8, 0
	v_or_b32_e32 v168, s79, v180
	v_mov_b32_e32 v169, s10
	v_readlane_b32 s8, v242, 28
	v_lshlrev_b64 v[2:3], 11, v[168:169]
	v_readlane_b32 s9, v242, 29
	v_lshrrev_b32_e32 v21, 5, v20
	s_lshl_b32 s74, s7, 1
	v_lshl_add_u64 v[2:3], s[8:9], 0, v[2:3]
	s_mov_b32 s75, s87
	v_lshl_add_u64 v[2:3], v[2:3], 0, s[74:75]
	v_lshlrev_b32_e32 v174, 4, v21
	v_mov_b32_e32 v175, v5
	v_lshl_add_u64 v[2:3], v[2:3], 0, v[174:175]
	global_load_dwordx4 v[6:9], v[2:3], off
	global_load_dwordx4 v[10:13], v[2:3], off offset:32
	global_load_dwordx4 v[14:17], v[2:3], off offset:64
	global_load_dwordx4 v[116:119], v[2:3], off offset:96
	v_lshlrev_b32_e32 v2, 1, v19
	v_and_b32_e32 v2, 32, v2
	v_add_u32_e32 v3, 0, v2
	v_lshlrev_b32_e32 v2, 2, v21
	v_lshrrev_b32_e32 v4, 2, v19
	v_and_or_b32 v4, v4, 3, v2
	v_lshlrev_b32_e32 v4, 6, v4
	s_and_b32 s2, s6, 0x3fffffc0
	v_add3_u32 v175, v3, v1, v4
	s_lshl_b32 s2, s2, 2
	v_lshrrev_b32_e32 v1, 3, v20
	v_and_or_b32 v3, s3, 32, v180
	s_add_i32 s89, s2, 0
	v_or_b32_e32 v168, s79, v1
	v_readlane_b32 s2, v242, 20
	v_lshlrev_b32_e32 v4, 3, v20
	v_lshlrev_b64 v[176:177], 11, v[168:169]
	v_readlane_b32 s3, v242, 21
	v_readlane_b32 s8, v242, 22
	v_and_b32_e32 v178, 56, v4
	v_lshl_add_u64 v[22:23], s[2:3], 0, v[176:177]
	v_readlane_b32 s9, v242, 23
	v_lshl_add_u64 v[22:23], v[22:23], 0, s[74:75]
	v_mov_b32_e32 v4, v178
	v_lshl_add_u64 v[26:27], s[8:9], 0, v[176:177]
	v_lshl_add_u64 v[22:23], v[22:23], 0, v[4:5]
	v_lshl_add_u64 v[26:27], v[26:27], 0, s[74:75]
	v_or_b32_e32 v34, 0x4000, v176
	v_mov_b32_e32 v35, v177
	global_load_dwordx2 v[24:25], v[22:23], off offset:64
	global_load_dwordx2 v[22:23], v[22:23], off
	v_lshl_add_u64 v[26:27], v[26:27], 0, v[4:5]
	v_lshl_add_u64 v[30:31], s[2:3], 0, v[34:35]
	global_load_dwordx2 v[28:29], v[26:27], off offset:64
	global_load_dwordx2 v[26:27], v[26:27], off
	v_lshl_add_u64 v[30:31], v[30:31], 0, s[74:75]
	v_lshl_add_u64 v[30:31], v[30:31], 0, v[4:5]
	global_load_dwordx2 v[32:33], v[30:31], off offset:64
	global_load_dwordx2 v[30:31], v[30:31], off
	v_lshl_add_u64 v[34:35], s[8:9], 0, v[34:35]
	v_lshl_add_u64 v[34:35], v[34:35], 0, s[74:75]
	v_lshl_add_u64 v[34:35], v[34:35], 0, v[4:5]
	global_load_dwordx2 v[36:37], v[34:35], off offset:64
	global_load_dwordx2 v[34:35], v[34:35], off
	v_or_b32_e32 v42, 0x8000, v176
	v_mov_b32_e32 v43, v177
	v_lshl_add_u64 v[38:39], s[2:3], 0, v[42:43]
	v_lshl_add_u64 v[38:39], v[38:39], 0, s[74:75]
	v_lshl_add_u64 v[38:39], v[38:39], 0, v[4:5]
	global_load_dwordx2 v[40:41], v[38:39], off offset:64
	global_load_dwordx2 v[38:39], v[38:39], off
	v_lshl_add_u64 v[42:43], s[8:9], 0, v[42:43]
	v_lshl_add_u64 v[42:43], v[42:43], 0, s[74:75]
	v_lshl_add_u64 v[42:43], v[42:43], 0, v[4:5]
	global_load_dwordx2 v[44:45], v[42:43], off offset:64
	global_load_dwordx2 v[42:43], v[42:43], off
	v_or_b32_e32 v50, 0xc000, v176
	v_mov_b32_e32 v51, v177
	v_lshl_add_u64 v[46:47], s[2:3], 0, v[50:51]
	v_lshl_add_u64 v[46:47], v[46:47], 0, s[74:75]
	v_lshl_add_u64 v[46:47], v[46:47], 0, v[4:5]
	global_load_dwordx2 v[48:49], v[46:47], off offset:64
	global_load_dwordx2 v[46:47], v[46:47], off
	v_lshl_add_u64 v[50:51], s[8:9], 0, v[50:51]
	v_lshl_add_u64 v[50:51], v[50:51], 0, s[74:75]
	v_lshl_add_u64 v[50:51], v[50:51], 0, v[4:5]
	global_load_dwordx2 v[52:53], v[50:51], off offset:64
	global_load_dwordx2 v[50:51], v[50:51], off
	s_add_i32 s89, s89, 0x1a000
	s_add_u32 s2, s79, 0x10000
	v_writelane_b32 v242, s10, 34
	s_addc_u32 s3, s10, 0
	v_or_b32_e32 v54, s2, v1
	v_mov_b32_e32 v55, s3
	v_readlane_b32 s2, v242, 26
	v_lshlrev_b64 v[54:55], 11, v[54:55]
	v_readlane_b32 s3, v242, 27
	s_lshl_b32 s92, s7, 2
	s_mov_b32 s93, s87
	v_lshl_add_u64 v[56:57], s[2:3], 0, v[54:55]
	v_readlane_b32 s2, v242, 43
	v_readlane_b32 s3, v242, 44
	v_lshl_add_u64 v[56:57], v[56:57], 0, s[92:93]
	v_lshlrev_b32_e32 v4, 1, v178
	v_lshl_add_u64 v[54:55], s[2:3], 0, v[54:55]
	v_lshl_add_u64 v[54:55], v[54:55], 0, s[92:93]
	v_lshl_add_u64 v[58:59], v[56:57], 0, v[4:5]
	v_lshl_add_u64 v[60:61], v[54:55], 0, v[4:5]
	v_or_b32_e32 v4, 32, v2
	v_cmp_gt_u32_e64 s[10:11], v4, v3
	v_or_b32_e32 v4, 33, v2
	v_cmp_gt_u32_e64 s[14:15], v4, v3
	v_or_b32_e32 v4, 2, v2
	v_cmp_gt_u32_e64 s[16:17], v4, v3
	v_or_b32_e32 v4, 34, v2
	v_cmp_gt_u32_e64 s[18:19], v4, v3
	v_or_b32_e32 v4, 3, v2
	v_cmp_gt_u32_e64 s[20:21], v4, v3
	v_or_b32_e32 v4, 35, v2
	v_cmp_gt_u32_e64 s[22:23], v4, v3
	v_or_b32_e32 v4, 8, v2
	s_mov_b64 s[2:3], 0x4000
	v_cmp_gt_u32_e64 s[24:25], v4, v3
	v_or_b32_e32 v4, 40, v2
	v_cmp_gt_u32_e64 s[26:27], v4, v3
	v_or_b32_e32 v4, 9, v2
	v_cmp_gt_u32_e64 s[28:29], v4, v3
	v_or_b32_e32 v4, 41, v2
	v_cmp_gt_u32_e64 s[30:31], v4, v3
	v_or_b32_e32 v4, 10, v2
	v_cmp_gt_u32_e64 s[34:35], v4, v3
	v_or_b32_e32 v4, 42, v2
	v_cmp_gt_u32_e64 s[36:37], v4, v3
	v_or_b32_e32 v4, 11, v2
	v_cmp_gt_u32_e64 s[38:39], v4, v3
	v_or_b32_e32 v4, 43, v2
	v_cmp_gt_u32_e64 s[40:41], v4, v3
	s_waitcnt vmcnt(0)
; __device__ __forceinline__ float bflo(unsigned w) { return __uint_as_float(w << 16); }
; __device__ __forceinline__ float bfhi(unsigned w) { return __uint_as_float(w & 0xffff0000u); }
; __device__ __forceinline__ void conv_load(ConvRegs& c, const Args& a, size_t rowq, int col, int lane) {
; #pragma unroll
;     for (int i = 0; i < 4; ++i) { const size_t grow = rowq + i * 8 + (lane >> 3);
;         c.k[i] = *(const u32x4*)((const bf16*)(a.ws + WS_K) + grow * D + col + (lane & 7) * 8); c.v[i] = *(const u32x4*)((const bf16*)(a.ws + WS_V) + grow * D + col + (lane & 7) * 8); }
; }
; template <int TYPE>
; __device__ __forceinline__ void conv_store(const ConvRegs& c, const Args& a, int l, int h, size_t rowq, int lane) {
; #pragma unroll
;     for (int i = 0; i < 4; ++i) { const size_t grow = rowq + i * 8 + (lane >> 3);
;         float* ko = a.out + (TYPE == 0 ? O_FKP : O_SKP) + ((size_t)l * MP + grow) * W + h * HD + (lane & 7) * 8;
;         float* vo = a.out + (TYPE == 0 ? O_FVP : O_SVP) + ((size_t)l * MP + grow) * W + h * HD + (lane & 7) * 8;
;         const u32x4 kw = c.k[i], vw = c.v[i];
;         __builtin_nontemporal_store((f32x4){bflo(kw.x), bfhi(kw.x), bflo(kw.y), bfhi(kw.y)}, (f32x4*)ko); __builtin_nontemporal_store((f32x4){bflo(kw.z), bfhi(kw.z), bflo(kw.w), bfhi(kw.w)}, (f32x4*)(ko + 4));
;         __builtin_nontemporal_store((f32x4){bflo(vw.x), bfhi(vw.x), bflo(vw.y), bfhi(vw.y)}, (f32x4*)vo); __builtin_nontemporal_store((f32x4){bflo(vw.z), bfhi(vw.z), bflo(vw.w), bfhi(vw.w)}, (f32x4*)(vo + 4)); }
; }
; __device__ __forceinline__ void prompt_unit_fox(const Args& a, int l, int b, int h, int qb, LAS unsigned char* lds) {
;     ...
;     FoxState st; st.m = 0.f; st.l = 0.f; st.mq = (bf16x8){}; st.o[0] = (f32x16){}; st.o[1] = (f32x16){};
;     PairP pp; bool pending = false;
; #pragma unroll
;     for (int i = 0; i < 8; ++i) pp.w[i] = (u32x4){0u, 0u, 0u, 0u};
;     { ConvRegs cv; conv_load(cv, a, rowb + q0 + wid * 32, col, lane); conv_store<0>(cv, a, l, h, rowb + q0 + wid * 32, lane); }
;     int slot = 0, pslot = 0;
	v_lshlrev_b32_e32 v54, 16, v22
	v_and_b32_e32 v55, 0xffff0000, v22
	v_lshlrev_b32_e32 v56, 16, v23
	v_and_b32_e32 v57, 0xffff0000, v23
	v_lshlrev_b32_e32 v22, 16, v24
	v_and_b32_e32 v23, 0xffff0000, v24
	v_lshlrev_b32_e32 v24, 16, v25
	v_and_b32_e32 v25, 0xffff0000, v25
	global_store_dwordx4 v[58:59], v[22:25], off offset:128
	v_or_b32_e32 v4, 16, v2
	v_cmp_gt_u32_e64 s[42:43], v4, v3
	v_lshlrev_b32_e32 v22, 16, v26
	v_and_b32_e32 v23, 0xffff0000, v26
	v_lshlrev_b32_e32 v24, 16, v27
	v_and_b32_e32 v25, 0xffff0000, v27
	global_store_dwordx4 v[60:61], v[22:25], off
	v_lshl_add_u64 v[26:27], v[58:59], 0, s[2:3]
	v_or_b32_e32 v4, 48, v2
	v_lshlrev_b32_e32 v22, 16, v28
	v_and_b32_e32 v23, 0xffff0000, v28
	v_lshlrev_b32_e32 v24, 16, v29
	v_and_b32_e32 v25, 0xffff0000, v29
	v_lshl_add_u64 v[28:29], v[60:61], 0, s[2:3]
	s_movk_i32 s2, 0x4000
	global_store_dwordx4 v[60:61], v[22:25], off offset:128
	v_cmp_gt_u32_e64 s[44:45], v4, v3
	v_or_b32_e32 v4, 17, v2
	v_lshlrev_b32_e32 v22, 16, v30
	v_and_b32_e32 v23, 0xffff0000, v30
	v_add_co_u32_e32 v30, vcc, s2, v58
	v_lshlrev_b32_e32 v24, 16, v31
	v_and_b32_e32 v25, 0xffff0000, v31
	v_addc_co_u32_e32 v31, vcc, 0, v59, vcc
	global_store_dwordx4 v[30:31], v[22:25], off
	v_cmp_gt_u32_e64 s[46:47], v4, v3
	v_or_b32_e32 v4, 49, v2
	v_lshlrev_b32_e32 v22, 16, v32
	v_and_b32_e32 v23, 0xffff0000, v32
	v_lshlrev_b32_e32 v24, 16, v33
	v_and_b32_e32 v25, 0xffff0000, v33
	global_store_dwordx4 v[26:27], v[22:25], off offset:128
	v_add_co_u32_e32 v26, vcc, s2, v60
	s_nop 0
	v_lshlrev_b32_e32 v22, 16, v34
	v_and_b32_e32 v23, 0xffff0000, v34
	v_lshlrev_b32_e32 v24, 16, v35
	v_and_b32_e32 v25, 0xffff0000, v35
	v_addc_co_u32_e32 v27, vcc, 0, v61, vcc
	global_store_dwordx4 v[26:27], v[22:25], off
	s_mov_b64 s[2:3], 0x8000
	v_lshl_add_u64 v[26:27], v[58:59], 0, s[2:3]
	v_lshlrev_b32_e32 v22, 16, v36
	v_and_b32_e32 v23, 0xffff0000, v36
	v_lshlrev_b32_e32 v24, 16, v37
	v_and_b32_e32 v25, 0xffff0000, v37
	global_store_dwordx4 v[28:29], v[22:25], off offset:128
	v_lshl_add_u64 v[28:29], v[60:61], 0, s[2:3]
	s_mov_b32 s2, 0x8000
	v_add_co_u32_e32 v30, vcc, s2, v58
	v_lshlrev_b32_e32 v22, 16, v38
	v_and_b32_e32 v23, 0xffff0000, v38
	v_lshlrev_b32_e32 v24, 16, v39
	v_and_b32_e32 v25, 0xffff0000, v39
	v_addc_co_u32_e32 v31, vcc, 0, v59, vcc
	global_store_dwordx4 v[30:31], v[22:25], off
	v_cmp_gt_u32_e64 s[48:49], v4, v3
	v_or_b32_e32 v4, 18, v2
	v_lshlrev_b32_e32 v22, 16, v40
	v_and_b32_e32 v23, 0xffff0000, v40
	v_lshlrev_b32_e32 v24, 16, v41
	v_and_b32_e32 v25, 0xffff0000, v41
	global_store_dwordx4 v[26:27], v[22:25], off offset:128
	v_add_co_u32_e32 v26, vcc, s2, v60
	v_cmp_gt_u32_e64 s[50:51], v4, v3
	v_or_b32_e32 v4, 50, v2
	v_lshlrev_b32_e32 v22, 16, v42
	v_and_b32_e32 v23, 0xffff0000, v42
	v_lshlrev_b32_e32 v24, 16, v43
	v_and_b32_e32 v25, 0xffff0000, v43
	v_addc_co_u32_e32 v27, vcc, 0, v61, vcc
	v_cmp_gt_u32_e64 s[52:53], v4, v3
	v_or_b32_e32 v4, 19, v2
	global_store_dwordx4 v[26:27], v[22:25], off
	s_mov_b64 s[2:3], 0xc000
	v_cmp_gt_u32_e64 s[54:55], v4, v3
	v_lshlrev_b32_e32 v22, 16, v44
	v_and_b32_e32 v23, 0xffff0000, v44
	v_lshlrev_b32_e32 v24, 16, v45
	v_and_b32_e32 v25, 0xffff0000, v45
	v_or_b32_e32 v4, 51, v2
	global_store_dwordx4 v[28:29], v[22:25], off offset:128
	v_lshl_add_u64 v[26:27], v[58:59], 0, s[2:3]
	v_lshl_add_u64 v[28:29], v[60:61], 0, s[2:3]
	s_mov_b32 s2, 0xc000
	v_cmp_gt_u32_e64 s[56:57], v4, v3
	v_or_b32_e32 v4, 24, v2
	v_add_co_u32_e32 v30, vcc, s2, v58
	v_cmp_gt_u32_e64 s[58:59], v4, v3
	v_or_b32_e32 v4, 56, v2
	v_lshlrev_b32_e32 v22, 16, v46
	v_and_b32_e32 v23, 0xffff0000, v46
	v_lshlrev_b32_e32 v24, 16, v47
	v_and_b32_e32 v25, 0xffff0000, v47
	v_addc_co_u32_e32 v31, vcc, 0, v59, vcc
	v_cmp_gt_u32_e64 s[60:61], v4, v3
	v_or_b32_e32 v4, 25, v2
	global_store_dwordx4 v[30:31], v[22:25], off
	v_cmp_gt_u32_e64 s[62:63], v4, v3
	v_or_b32_e32 v4, 57, v2
	v_lshlrev_b32_e32 v22, 16, v48
	v_and_b32_e32 v23, 0xffff0000, v48
	v_lshlrev_b32_e32 v24, 16, v49
	v_and_b32_e32 v25, 0xffff0000, v49
	global_store_dwordx4 v[26:27], v[22:25], off offset:128
	v_add_co_u32_e32 v26, vcc, s2, v60
	s_add_i32 s2, 0, 0x18000
	v_cmp_gt_u32_e64 s[64:65], v4, v3
	v_or_b32_e32 v4, 26, v2
	v_lshlrev_b32_e32 v22, 16, v50
	v_and_b32_e32 v23, 0xffff0000, v50
	v_lshlrev_b32_e32 v24, 16, v51
	v_and_b32_e32 v25, 0xffff0000, v51
	v_addc_co_u32_e32 v27, vcc, 0, v61, vcc
	v_add_u32_e32 v186, s2, v174
	s_add_i32 s2, 0, 0x1a800
	v_cmp_gt_u32_e64 s[66:67], v4, v3
	v_or_b32_e32 v4, 58, v2
	v_mov_b32_e32 v66, v5
	v_mov_b32_e32 v67, v5
	global_store_dwordx4 v[58:59], v[54:57], off
	global_store_dwordx4 v[26:27], v[22:25], off
	s_bitcmp1_b32 s6, 7
	v_cmp_gt_u32_e64 s[6:7], 32, v20
	v_lshlrev_b32_e32 v22, 16, v52
	v_and_b32_e32 v23, 0xffff0000, v52
	v_lshlrev_b32_e32 v24, 16, v53
	v_and_b32_e32 v25, 0xffff0000, v53
	v_cmp_gt_u32_e64 s[8:9], v2, v3
	v_cmp_lt_u32_e64 s[12:13], v2, v3
	v_cmp_gt_u32_e64 s[68:69], v4, v3
	v_or_b32_e32 v4, 27, v2
	v_or_b32_e32 v2, 59, v2
	v_mov_b32_e32 v52, v5
	v_mov_b32_e32 v53, v5
	v_mov_b32_e32 v54, v5
	v_mov_b32_e32 v55, v5
	v_mov_b32_e32 v56, v5
	v_mov_b32_e32 v57, v5
	v_mov_b32_e32 v58, v5
	v_mov_b32_e32 v59, v5
	v_mov_b32_e32 v60, v5
	v_mov_b32_e32 v61, v5
	v_mov_b32_e32 v62, v5
	v_mov_b32_e32 v63, v5
	v_mov_b32_e32 v64, v5
	v_mov_b32_e32 v65, v5
	v_mov_b64_e32 v[82:83], v[66:67]
	s_mov_b32 s75, 0
	v_lshl_add_u32 v188, v180, 3, s2
	s_cselect_b64 s[94:95], -1, 0
	v_lshlrev_b32_e32 v182, 10, v21
	v_lshlrev_b32_e32 v189, 4, v180
	v_cndmask_b32_e64 v122, 0, v183, s[6:7]
	v_cndmask_b32_e64 v121, 0, -1.0, s[6:7]
	v_mov_b32_e32 v120, v5
	v_mov_b32_e32 v123, v5
	v_cmp_gt_u32_e64 s[70:71], v4, v3
	v_cmp_gt_u32_e64 s[72:73], v2, v3
	v_lshl_add_u32 v184, v180, 2, s89
	v_mov_b32_e32 v156, v5
	v_mov_b32_e32 v157, v5
	v_mov_b32_e32 v158, v5
	v_mov_b32_e32 v159, v5
	v_mov_b32_e32 v192, 0
	s_mov_b64 s[2:3], 0
	v_mov_b32_e32 v124, 0
	v_mov_b32_e32 v125, 0
	v_mov_b32_e32 v126, 0
	v_mov_b32_e32 v127, 0
	v_mov_b32_e32 v128, 0
	v_mov_b32_e32 v129, 0
	v_mov_b32_e32 v130, 0
	v_mov_b32_e32 v131, 0
	v_mov_b32_e32 v132, 0
	v_mov_b32_e32 v133, 0
	v_mov_b32_e32 v134, 0
	v_mov_b32_e32 v135, 0
	v_mov_b32_e32 v136, 0
	v_mov_b32_e32 v137, 0
	v_mov_b32_e32 v138, 0
	v_mov_b32_e32 v139, 0
	v_mov_b32_e32 v140, 0
	v_mov_b32_e32 v141, 0
	v_mov_b32_e32 v142, 0
	v_mov_b32_e32 v143, 0
	v_mov_b32_e32 v144, 0
	v_mov_b32_e32 v145, 0
	v_mov_b32_e32 v146, 0
	v_mov_b32_e32 v147, 0
	v_mov_b32_e32 v148, 0
	v_mov_b32_e32 v149, 0
	v_mov_b32_e32 v150, 0
	v_mov_b32_e32 v151, 0
	v_mov_b32_e32 v152, 0
	v_mov_b32_e32 v153, 0
	v_mov_b32_e32 v154, 0
	v_mov_b32_e32 v155, 0
	v_cndmask_b32_e64 v2, 0, v185, s[6:7]
	s_mov_b32 s93, 0
	v_mov_b64_e32 v[80:81], v[64:65]
	v_mov_b64_e32 v[78:79], v[62:63]
	v_mov_b64_e32 v[76:77], v[60:61]
	v_mov_b64_e32 v[74:75], v[58:59]
	v_mov_b64_e32 v[72:73], v[56:57]
	v_mov_b64_e32 v[70:71], v[54:55]
	v_mov_b64_e32 v[68:69], v[52:53]
	v_mov_b32_e32 v193, 0
	global_store_dwordx4 v[28:29], v[22:25], off offset:128
	s_waitcnt vmcnt(16) lgkmcnt(0)
	s_barrier
; #define ATT_WAIT_BAR() asm volatile("s_waitcnt vmcnt(0) lgkmcnt(0)\n\ts_barrier" ::: "memory")
; __device__ __forceinline__ void prompt_unit_fox(const Args& a, int l, int b, int h, int qb, LAS unsigned char* lds) {
;     ...
;     FoxState st; st.m = 0.f; st.l = 0.f; st.mq = (bf16x8){}; st.o[0] = (f32x16){}; st.o[1] = (f32x16){};
;     PairP pp; bool pending = false;
; #pragma unroll
;     for (int i = 0; i < 8; ++i) pp.w[i] = (u32x4){0u, 0u, 0u, 0u};
;     { ConvRegs cv; conv_load(cv, a, rowb + q0 + wid * 32, col, lane); conv_store<0>(cv, a, l, h, rowb + q0 + wid * 32, lane); }
;     int slot = 0, pslot = 0;
;     ...
;         ATT_WAIT_BAR();
	v_mov_b64_e32 v[20:21], 0
	v_mov_b64_e32 v[22:23], 0
	v_mov_b64_e32 v[24:25], 0
	v_mov_b64_e32 v[26:27], 0
	v_mov_b64_e32 v[28:29], 0
	v_mov_b64_e32 v[30:31], 0
	v_mov_b64_e32 v[32:33], 0
	v_mov_b64_e32 v[34:35], 0
	v_mov_b64_e32 v[36:37], 0
	v_mov_b64_e32 v[38:39], 0
	v_mov_b64_e32 v[40:41], 0
	v_mov_b64_e32 v[42:43], 0
	v_mov_b64_e32 v[44:45], 0
	v_mov_b64_e32 v[46:47], 0
	v_mov_b64_e32 v[48:49], 0
	v_mov_b64_e32 v[50:51], 0
	s_branch .Lfox_top_l1

; __device__ __forceinline__ void prompt_unit_fox(const Args& a, int l, int b, int h, int qb, LAS unsigned char* lds) {
;     ...
;         if (jp >= 1) ATT_DMA2(jp - 1, slot == 2 ? 0 : slot + 1);
.Lfox_top_l1:
	s_cmp_lg_u32 s78, 0
	s_cbranch_scc0 .LBB0_995
	s_add_i32 s80, s78, -1
	s_mov_b32 s81, s87
	s_lshl_b32 s33, s93, 14
	s_lshl_b64 s[80:81], s[80:81], 18
	s_add_i32 s76, s33, 0x4000
	s_cmp_lg_u32 s93, 2
	s_cselect_b32 s76, s76, 0
	v_lshl_add_u64 v[244:245], v[170:171], 0, s[80:81]
	s_add_i32 s77, s96, s76
	s_mov_b32 s82, m0
	s_mov_b32 m0, s77
	s_nop 0
	global_load_lds_dwordx4 v[244:245], off
	s_mov_b32 m0, s82
	s_mov_b64 vcc, 0x20000
	v_lshl_add_u64 v[244:245], v[244:245], 0, vcc
	s_add_i32 s77, s97, s76
	s_mov_b32 s82, m0
	s_mov_b32 m0, s77
	s_nop 0
	global_load_lds_dwordx4 v[244:245], off
	s_mov_b32 m0, s82
	v_lshl_add_u64 v[244:245], v[172:173], 0, s[80:81]
	s_add_i32 s77, s84, s76
	s_mov_b32 s80, m0
	s_mov_b32 m0, s77
	s_nop 0
	global_load_lds_dwordx4 v[244:245], off
	s_mov_b32 m0, s80
	v_lshl_add_u64 v[244:245], v[244:245], 0, vcc
	s_add_i32 s76, s85, s76
	s_mov_b32 s77, m0
	s_mov_b32 m0, s76
	s_nop 0
	global_load_lds_dwordx4 v[244:245], off
	s_mov_b32 m0, s77
	s_cbranch_execnz .LBB0_967

; __device__ __forceinline__ void vfrags(VFrags& v, lds_cptr vp) {
; #pragma unroll
;     ...
; }
; __device__ __forceinline__ void pv(f32x16 (&o)[2], const VFrags& v, const u32x4& pw0, const u32x4& pw1, const u32x4& pw2, const u32x4& pw3) {
;     ...
;     o[0] = __builtin_amdgcn_mfma_f32_32x32x16_bf16(__builtin_bit_cast(bf16x8, pw0), ATT_VF(0), o[0], 0, 0, 0);
;     o[1] = __builtin_amdgcn_mfma_f32_32x32x16_bf16(__builtin_bit_cast(bf16x8, pw0), ATT_VF(4), o[1], 0, 0, 0);
;     o[0] = __builtin_amdgcn_mfma_f32_32x32x16_bf16(__builtin_bit_cast(bf16x8, pw1), ATT_VF(1), o[0], 0, 0, 0);
;     o[1] = __builtin_amdgcn_mfma_f32_32x32x16_bf16(__builtin_bit_cast(bf16x8, pw1), ATT_VF(5), o[1], 0, 0, 0);
;     o[0] = __builtin_amdgcn_mfma_f32_32x32x16_bf16(__builtin_bit_cast(bf16x8, pw2), ATT_VF(2), o[0], 0, 0, 0);
;     o[1] = __builtin_amdgcn_mfma_f32_32x32x16_bf16(__builtin_bit_cast(bf16x8, pw2), ATT_VF(6), o[1], 0, 0, 0);
;     o[0] = __builtin_amdgcn_mfma_f32_32x32x16_bf16(__builtin_bit_cast(bf16x8, pw3), ATT_VF(3), o[0], 0, 0, 0);
;     o[1] = __builtin_amdgcn_mfma_f32_32x32x16_bf16(__builtin_bit_cast(bf16x8, pw3), ATT_VF(7), o[1], 0, 0, 0);
;     ...
; }
; __device__ __forceinline__ void fox_pair_pv(FoxState& st, const PairP& pp, lds_cptr vpB) {
;     { VFrags vf; vfrags(vf, vpB + 8192); pv(st.o, vf, pp.w[0], pp.w[1], pp.w[2], pp.w[3]); }
;     { VFrags vf; vfrags(vf, vpB); pv(st.o, vf, pp.w[4], pp.w[5], pp.w[6], pp.w[7]); }
; }
.LBB0_967:
	s_andn2_b64 vcc, exec, s[2:3]
	s_cbranch_vccnz .LBB0_969
	v_lshl_add_u32 v3, s75, 14, v175
	ds_read_b64_tr_b16 v[84:85], v3 offset:57344
	ds_read_b64_tr_b16 v[86:87], v3 offset:57856
	ds_read_b64_tr_b16 v[88:89], v3 offset:61440
	ds_read_b64_tr_b16 v[90:91], v3 offset:61952
	ds_read_b64_tr_b16 v[92:93], v3 offset:58368
	ds_read_b64_tr_b16 v[94:95], v3 offset:58880
	ds_read_b64_tr_b16 v[96:97], v3 offset:62464
	ds_read_b64_tr_b16 v[98:99], v3 offset:62976
	ds_read_b64_tr_b16 v[100:101], v3 offset:59392
	ds_read_b64_tr_b16 v[102:103], v3 offset:59904
	ds_read_b64_tr_b16 v[104:105], v3 offset:63488
	ds_read_b64_tr_b16 v[106:107], v3 offset:64000
	ds_read_b64_tr_b16 v[108:109], v3 offset:60416
	ds_read_b64_tr_b16 v[110:111], v3 offset:60928
	s_waitcnt lgkmcnt(12)
	v_mfma_f32_32x32x16_bf16 v[20:35], v[152:155], v[84:87], v[20:35]
	ds_read_b64_tr_b16 v[112:113], v3 offset:64512
	ds_read_b64_tr_b16 v[114:115], v3 offset:65024
	s_waitcnt lgkmcnt(12)
	v_mfma_f32_32x32x16_bf16 v[36:51], v[152:155], v[88:91], v[36:51]
	ds_read_b64_tr_b16 v[84:85], v3 offset:49152
	ds_read_b64_tr_b16 v[86:87], v3 offset:49664
	s_waitcnt lgkmcnt(12)
	v_mfma_f32_32x32x16_bf16 v[20:35], v[148:151], v[92:95], v[20:35]
	ds_read_b64_tr_b16 v[88:89], v3 offset:53248
	ds_read_b64_tr_b16 v[90:91], v3 offset:53760
	s_waitcnt lgkmcnt(12)
	v_mfma_f32_32x32x16_bf16 v[36:51], v[148:151], v[96:99], v[36:51]
	ds_read_b64_tr_b16 v[92:93], v3 offset:50176
	ds_read_b64_tr_b16 v[94:95], v3 offset:50688
	s_waitcnt lgkmcnt(12)
	v_mfma_f32_32x32x16_bf16 v[20:35], v[144:147], v[100:103], v[20:35]
	ds_read_b64_tr_b16 v[96:97], v3 offset:54272
	ds_read_b64_tr_b16 v[98:99], v3 offset:54784
	s_waitcnt lgkmcnt(12)
	v_mfma_f32_32x32x16_bf16 v[36:51], v[144:147], v[104:107], v[36:51]
	ds_read_b64_tr_b16 v[100:101], v3 offset:51200
	ds_read_b64_tr_b16 v[102:103], v3 offset:51712
	s_waitcnt lgkmcnt(12)
	v_mfma_f32_32x32x16_bf16 v[20:35], v[140:143], v[108:111], v[20:35]
	ds_read_b64_tr_b16 v[104:105], v3 offset:55296
	ds_read_b64_tr_b16 v[106:107], v3 offset:55808
	s_waitcnt lgkmcnt(12)
	v_mfma_f32_32x32x16_bf16 v[36:51], v[140:143], v[112:115], v[36:51]
	ds_read_b64_tr_b16 v[108:109], v3 offset:52224
	ds_read_b64_tr_b16 v[110:111], v3 offset:52736
	s_waitcnt lgkmcnt(12)
	v_mfma_f32_32x32x16_bf16 v[20:35], v[136:139], v[84:87], v[20:35]
	ds_read_b64_tr_b16 v[112:113], v3 offset:56320
	ds_read_b64_tr_b16 v[114:115], v3 offset:56832
	s_waitcnt lgkmcnt(12)
	v_mfma_f32_32x32x16_bf16 v[36:51], v[136:139], v[88:91], v[36:51]
	s_waitcnt lgkmcnt(10)
	v_mfma_f32_32x32x16_bf16 v[20:35], v[132:135], v[92:95], v[20:35]
	s_waitcnt lgkmcnt(8)
	v_mfma_f32_32x32x16_bf16 v[36:51], v[132:135], v[96:99], v[36:51]
	s_waitcnt lgkmcnt(6)
	v_mfma_f32_32x32x16_bf16 v[20:35], v[128:131], v[100:103], v[20:35]
	s_waitcnt lgkmcnt(4)
	v_mfma_f32_32x32x16_bf16 v[36:51], v[128:131], v[104:107], v[36:51]
	s_waitcnt lgkmcnt(2)
	v_mfma_f32_32x32x16_bf16 v[20:35], v[124:127], v[108:111], v[20:35]
	s_waitcnt lgkmcnt(0)
	v_mfma_f32_32x32x16_bf16 v[36:51], v[124:127], v[112:115], v[36:51]
.LBB0_969:
	s_nop 9
	s_add_i32 s80, s33, 0
	s_lshl_b32 s81, s78, 7
	v_add_u32_e32 v190, s33, v175
	s_cmp_ge_i32 s78, s0
	s_mov_b64 s[2:3], -1
	s_cbranch_scc0 .LBB0_980
	v_mov_b64_e32 v[66:67], v[50:51]
	v_mov_b64_e32 v[82:83], v[34:35]
	v_mov_b64_e32 v[162:163], v[158:159]
	s_cmp_lg_u32 s78, s0
	v_mov_b64_e32 v[64:65], v[48:49]
	v_mov_b64_e32 v[62:63], v[46:47]
	v_mov_b64_e32 v[60:61], v[44:45]
	v_mov_b64_e32 v[58:59], v[42:43]
	v_mov_b64_e32 v[56:57], v[40:41]
	v_mov_b64_e32 v[54:55], v[38:39]
	v_mov_b64_e32 v[52:53], v[36:37]
	v_mov_b64_e32 v[80:81], v[32:33]
	v_mov_b64_e32 v[78:79], v[30:31]
	v_mov_b64_e32 v[76:77], v[28:29]
	v_mov_b64_e32 v[74:75], v[26:27]
	v_mov_b64_e32 v[72:73], v[24:25]
	v_mov_b64_e32 v[70:71], v[22:23]
	v_mov_b64_e32 v[68:69], v[20:21]
	v_mov_b64_e32 v[160:161], v[156:157]
	v_mov_b32_e32 v194, v192
	v_mov_b32_e32 v191, v193
	s_cbranch_scc1 .LBB0_979
	v_lshl_add_u32 v196, s81, 2, v186
	s_andn2_b64 vcc, exec, s[94:95]
	v_add3_u32 v195, s80, v182, v189
	s_cbranch_vccnz .LBB0_977
	ds_read_b128 v[68:71], v196 offset:256
	ds_read_b128 v[72:75], v196 offset:288
	ds_read_b128 v[76:79], v196 offset:320
	ds_read_b128 v[80:83], v196 offset:352
	ds_read_b128 v[52:55], v196 offset:384
	ds_read_b128 v[56:59], v196 offset:416
	ds_read_b128 v[60:63], v196 offset:448
	ds_read_b128 v[64:67], v196 offset:480
	ds_read_b128 v[84:87], v195 offset:8192
	s_waitcnt lgkmcnt(5)
	v_mfma_f32_32x32x16_bf16 v[68:83], v[120:123], v[156:159], v[68:83]
	s_waitcnt lgkmcnt(0)
	v_mfma_f32_32x32x16_bf16 v[68:83], v[84:87], v[6:9], v[68:83]
	ds_read_b128 v[84:87], v195 offset:8704
	v_mfma_f32_32x32x16_bf16 v[52:67], v[120:123], v[156:159], v[52:67]
	s_waitcnt lgkmcnt(0)
	v_mfma_f32_32x32x16_bf16 v[52:67], v[84:87], v[6:9], v[52:67]
	ds_read_b128 v[84:87], v195 offset:10240
	s_waitcnt lgkmcnt(0)
	v_mfma_f32_32x32x16_bf16 v[68:83], v[84:87], v[10:13], v[68:83]
	ds_read_b128 v[84:87], v195 offset:10752
	s_waitcnt lgkmcnt(0)
	v_mfma_f32_32x32x16_bf16 v[52:67], v[84:87], v[10:13], v[52:67]
	ds_read_b128 v[84:87], v195 offset:12288
	s_waitcnt lgkmcnt(0)
	v_mfma_f32_32x32x16_bf16 v[68:83], v[84:87], v[14:17], v[68:83]
	ds_read_b128 v[84:87], v195 offset:12800
	s_waitcnt lgkmcnt(0)
	v_mfma_f32_32x32x16_bf16 v[52:67], v[84:87], v[14:17], v[52:67]
	ds_read_b128 v[84:87], v195 offset:14336
	s_waitcnt lgkmcnt(0)
	v_mfma_f32_32x32x16_bf16 v[68:83], v[84:87], v[116:119], v[68:83]
	ds_read_b128 v[84:87], v195 offset:14848
	s_waitcnt lgkmcnt(0)
; #define LAS __attribute__((address_space(3)))
; __device__ __forceinline__ int crow(int r, int hi) { return (r & 3) + 8 * (r >> 2) + 4 * hi; }
; __device__ __forceinline__ float swap_max(float m) { auto rr = __builtin_amdgcn_permlane32_swap(__float_as_uint(m), __float_as_uint(m), false, false); return fmaxf(__uint_as_float(rr[0]), __uint_as_float(rr[1])); }
; __device__ __forceinline__ float max3f(float a, float b, float c) { return __builtin_fmaxf(__builtin_fmaxf(a, b), c); }
; __device__ __forceinline__ float fadd_s(float a, float b) { float r = a + b; asm volatile("" : "+v"(r)); return r; }
; #define ATT_LDS_WAIT() asm volatile("s_waitcnt lgkmcnt(0)" ::: "memory")
;     ...
;     if (masked) {
;         asm volatile("; masked tile" ::: "memory");
; #pragma unroll
;         for (int r = 0; r < 16; ++r) { const int kv = crow(r, hi); if (kv >= qlim) p0[r] = NEG; if (kv + 32 >= qlim) p1[r] = NEG; }
;     }
;     float rm = max3f(p0[0], p1[0], p0[1]), rm2 = max3f(p1[1], p0[2], p1[2]);
; #pragma unroll
;     for (int r = 3; r < 15; r += 2) { rm = max3f(rm, p0[r], p1[r]); rm2 = max3f(rm2, p0[r + 1], p1[r + 1]); }
;     rm = max3f(rm, p0[15], p1[15]); rm = swap_max(max3f(rm, rm2, rm2));
;     if (first || __any(rm > FOX_THR)) {
;         const float dl = first ? rm : fmaxf(rm, 0.f);
;         st.m += dl; st.mq = make_mq(st.m, hi);
; #pragma unroll
;         for (int r = 0; r < 16; ++r) { p0[r] -= dl; p1[r] -= dl; }
;         if (!first) {
;             const float f = __builtin_amdgcn_exp2f(-dl);
;             st.l *= f;
;             if (hi == 0) wsf[r32] = f;
;             ATT_LDS_WAIT();
; #pragma unroll
;             for (int g = 0; g < 4; ++g) { const f32x4 fv = *(const LAS f32x4*)(wsf + 8 * g + 4 * hi);
; #pragma unroll
;                 for (int i = 0; i < 4; ++i) { st.o[0][4 * g + i] *= fv[i]; st.o[1][4 * g + i] *= fv[i]; } }
;         }
;     }
;     __builtin_amdgcn_sched_barrier(0);
;     VFrags vf; vfrags(vf, vp);
;     float sacc = 0.f, sacc2 = 0.f;
; #pragma unroll
;     for (int r = 0; r < 16; ++r) { p0[r] = __builtin_amdgcn_exp2f(p0[r]); p1[r] = __builtin_amdgcn_exp2f(p1[r]); sacc = fadd_s(sacc, p0[r]); sacc2 = fadd_s(sacc2, p1[r]); }
	v_mfma_f32_32x32x16_bf16 v[52:67], v[84:87], v[116:119], v[52:67]
	s_and_b64 vcc, s[70:71], s[66:67]
	s_nop 7
	v_cndmask_b32_e32 v82, v82, v18, vcc
	s_and_b64 vcc, vcc, s[62:63]
	v_cndmask_b32_e32 v81, v81, v18, vcc
	s_and_b64 vcc, vcc, s[58:59]
	v_cndmask_b32_e32 v80, v80, v18, vcc
	s_and_b64 vcc, vcc, s[54:55]
	v_cndmask_b32_e32 v79, v79, v18, vcc
	s_and_b64 vcc, vcc, s[50:51]
	v_cndmask_b32_e32 v78, v78, v18, vcc
	s_and_b64 vcc, vcc, s[46:47]
	v_cndmask_b32_e32 v77, v77, v18, vcc
	s_and_b64 vcc, vcc, s[42:43]
	v_cndmask_b32_e32 v76, v76, v18, vcc
	s_and_b64 vcc, vcc, s[38:39]
	v_cndmask_b32_e32 v75, v75, v18, vcc
	s_and_b64 vcc, vcc, s[34:35]
	v_cndmask_b32_e32 v74, v74, v18, vcc
	s_and_b64 vcc, vcc, s[28:29]
	v_cndmask_b32_e32 v73, v73, v18, vcc
	s_and_b64 vcc, vcc, s[24:25]
	v_cndmask_b32_e64 v3, v68, v18, s[8:9]
	v_cndmask_b32_e32 v72, v72, v18, vcc
	s_and_b64 vcc, vcc, s[20:21]
	v_cndmask_b32_e64 v3, v3, v68, s[12:13]
	v_cndmask_b32_e64 v4, v18, v69, s[12:13]
	v_cndmask_b32_e32 v71, v71, v18, vcc
	s_and_b64 vcc, vcc, s[16:17]
	v_cndmask_b32_e32 v69, v69, v4, vcc
	v_cndmask_b32_e32 v68, v68, v3, vcc
	v_cndmask_b32_e32 v70, v70, v18, vcc
	s_and_b64 vcc, s[72:73], s[68:69]
	v_cndmask_b32_e32 v66, v66, v18, vcc
	s_and_b64 vcc, vcc, s[64:65]
	v_cndmask_b32_e32 v65, v65, v18, vcc
	s_and_b64 vcc, vcc, s[60:61]
	v_cndmask_b32_e32 v64, v64, v18, vcc
	s_and_b64 vcc, vcc, s[56:57]
	v_cndmask_b32_e32 v63, v63, v18, vcc
	s_and_b64 vcc, vcc, s[52:53]
	v_cndmask_b32_e32 v62, v62, v18, vcc
	s_and_b64 vcc, vcc, s[48:49]
	v_cndmask_b32_e32 v61, v61, v18, vcc
	s_and_b64 vcc, vcc, s[44:45]
	v_cndmask_b32_e32 v60, v60, v18, vcc
	s_and_b64 vcc, vcc, s[40:41]
	v_cndmask_b32_e32 v59, v59, v18, vcc
	s_and_b64 vcc, vcc, s[36:37]
	v_cndmask_b32_e32 v58, v58, v18, vcc
	s_and_b64 vcc, vcc, s[30:31]
	v_cndmask_b32_e32 v57, v57, v18, vcc
	s_and_b64 vcc, vcc, s[26:27]
	v_cndmask_b32_e32 v56, v56, v18, vcc
	s_and_b64 vcc, vcc, s[22:23]
	v_cndmask_b32_e32 v55, v55, v18, vcc
	s_and_b64 vcc, vcc, s[18:19]
	v_cndmask_b32_e32 v54, v54, v18, vcc
	s_and_b64 vcc, vcc, s[14:15]
	v_cndmask_b32_e32 v53, v53, v18, vcc
	s_and_b64 vcc, vcc, s[10:11]
	v_cndmask_b32_e32 v52, v52, v18, vcc
	v_max_f32_e32 v3, v68, v68
	v_max_f32_e32 v4, v52, v52
	v_max_f32_e32 v3, v3, v4
	v_max3_f32 v4, v53, v70, v54
	v_max3_f32 v3, v3, v69, v71
	v_max3_f32 v4, v4, v72, v56
	v_max3_f32 v3, v3, v55, v73
	v_max3_f32 v4, v4, v74, v58
	v_max3_f32 v3, v3, v57, v75
	v_max3_f32 v4, v4, v76, v60
	v_max3_f32 v3, v3, v59, v77
	v_max3_f32 v4, v4, v78, v62
	v_max3_f32 v3, v3, v61, v79
	v_cndmask_b32_e64 v83, v83, v18, s[70:71]
	v_max3_f32 v4, v4, v80, v64
	v_max3_f32 v3, v3, v63, v81
	v_cndmask_b32_e64 v67, v67, v18, s[72:73]
	v_max3_f32 v4, v4, v82, v66
	v_max3_f32 v3, v3, v65, v83
	v_max3_f32 v3, v3, v67, v4
	v_mov_b32_e32 v4, v3
	s_nop 1
	v_permlane32_swap_b32_e32 v3, v4
	v_max_f32_e32 v4, v4, v4
	v_max_f32_e32 v3, v3, v3
	v_max_f32_e32 v84, v3, v4
	v_add_f32_e32 v191, v193, v84
	v_cvt_pk_bf16_f32 v3, v191, 0
	v_lshlrev_b32_e32 v3, 16, v3
	v_sub_f32_e32 v4, v191, v3
	v_cvt_pk_bf16_f32 v85, v4, 0
	v_lshlrev_b32_e32 v85, 16, v85
	v_sub_f32_e32 v4, v4, v85
	v_cvt_pk_bf16_f32 v3, 1.0, v3
	v_cvt_pk_bf16_f32 v4, v85, v4
	v_cndmask_b32_e64 v4, 0, v4, s[6:7]
	v_cndmask_b32_e64 v3, 0, v3, s[6:7]
	v_sub_f32_e32 v68, v68, v84
	v_sub_f32_e32 v112, v52, v84
	v_sub_f32_e32 v69, v69, v84
	v_sub_f32_e32 v113, v53, v84
	v_sub_f32_e32 v70, v70, v84
	v_sub_f32_e32 v114, v54, v84
	v_sub_f32_e32 v71, v71, v84
	v_sub_f32_e32 v115, v55, v84
	v_sub_f32_e32 v72, v72, v84
	v_sub_f32_e32 v56, v56, v84
	v_sub_f32_e32 v73, v73, v84
	v_sub_f32_e32 v57, v57, v84
	v_sub_f32_e32 v74, v74, v84
	v_sub_f32_e32 v58, v58, v84
	v_sub_f32_e32 v75, v75, v84
	v_sub_f32_e32 v59, v59, v84
	v_sub_f32_e32 v76, v76, v84
	v_sub_f32_e32 v60, v60, v84
	v_sub_f32_e32 v77, v77, v84
	v_sub_f32_e32 v61, v61, v84
	v_sub_f32_e32 v78, v78, v84
	v_sub_f32_e32 v62, v62, v84
	v_sub_f32_e32 v79, v79, v84
	v_sub_f32_e32 v63, v63, v84
	v_sub_f32_e32 v80, v80, v84
	v_sub_f32_e32 v64, v64, v84
	v_sub_f32_e32 v81, v81, v84
	v_sub_f32_e32 v65, v65, v84
	v_sub_f32_e32 v82, v82, v84
	v_sub_f32_e32 v66, v66, v84
	v_sub_f32_e32 v83, v83, v84
	v_sub_f32_e32 v67, v67, v84
	v_exp_f32_e32 v68, v68
	v_exp_f32_e32 v164, v112
	v_exp_f32_e32 v69, v69
	v_exp_f32_e32 v165, v113
	v_add_f32_e32 v112, 0, v68
	v_exp_f32_e32 v70, v70
	ds_read_b64_tr_b16 v[52:53], v190 offset:57344
	ds_read_b64_tr_b16 v[54:55], v190 offset:57856
	ds_read_b64_tr_b16 v[84:85], v190 offset:58368
	ds_read_b64_tr_b16 v[86:87], v190 offset:58880
	ds_read_b64_tr_b16 v[88:89], v190 offset:59392
	ds_read_b64_tr_b16 v[90:91], v190 offset:59904
	ds_read_b64_tr_b16 v[92:93], v190 offset:60416
	ds_read_b64_tr_b16 v[94:95], v190 offset:60928
	ds_read_b64_tr_b16 v[96:97], v190 offset:61440
	ds_read_b64_tr_b16 v[98:99], v190 offset:61952
	ds_read_b64_tr_b16 v[100:101], v190 offset:62464
	ds_read_b64_tr_b16 v[102:103], v190 offset:62976
	ds_read_b64_tr_b16 v[104:105], v190 offset:63488
	ds_read_b64_tr_b16 v[106:107], v190 offset:64000
	ds_read_b64_tr_b16 v[108:109], v190 offset:64512
	ds_read_b64_tr_b16 v[110:111], v190 offset:65024
	v_exp_f32_e32 v166, v114
	v_add_f32_e32 v160, 0, v164
	v_add_f32_e32 v112, v112, v69
	v_exp_f32_e32 v71, v71
	v_exp_f32_e32 v167, v115
	v_add_f32_e32 v113, v160, v165
	v_add_f32_e32 v112, v112, v70
	v_exp_f32_e32 v72, v72
	v_add_f32_e32 v113, v113, v166
	v_exp_f32_e32 v56, v56
	v_add_f32_e32 v112, v112, v71
	v_exp_f32_e32 v73, v73
	v_add_f32_e32 v113, v113, v167
	v_exp_f32_e32 v57, v57
	v_add_f32_e32 v112, v112, v72
	v_exp_f32_e32 v74, v74
	v_add_f32_e32 v113, v113, v56
	v_exp_f32_e32 v58, v58
; __device__ __forceinline__ int crow(int r, int hi) { return (r & 3) + 8 * (r >> 2) + 4 * hi; }
; __device__ __forceinline__ unsigned cvtpk(float lo, float hi) { f32x2 v = {lo, hi}; bf16x2_t b = __builtin_convertvector(v, bf16x2_t); return __builtin_bit_cast(unsigned, b); }
; __device__ __forceinline__ float max3f(float a, float b, float c) { return __builtin_fmaxf(__builtin_fmaxf(a, b), c); }
;     bf16x8 kf[8]; kfrags(kf, kslot, r32, hi);
;     f32x16 p0, p1;
; #pragma unroll
;     for (int g = 0; g < 4; ++g) { const f32x4 c0 = ld4(ckt + 8 * g), c1 = ld4(ckt + 32 + 8 * g);
; #pragma unroll
;         for (int i = 0; i < 4; ++i) { p0[4 * g + i] = c0[i]; p1[4 * g + i] = c1[i]; } }
;     u32x4 kn = {0u, 0xBF800000u, 0xBF80BF80u, 0u}; if (hi) { kn.y = 0u; kn.z = 0u; }
;     const bf16x8 kneg = __builtin_bit_cast(bf16x8, kn);
;     p0 = __builtin_amdgcn_mfma_f32_32x32x16_bf16(kneg, st.mq, p0, 0, 0, 0);
;     p1 = __builtin_amdgcn_mfma_f32_32x32x16_bf16(kneg, st.mq, p1, 0, 0, 0);
; #pragma unroll
;     for (int d0 = 0; d0 < 4; ++d0) {
;         p0 = __builtin_amdgcn_mfma_f32_32x32x16_bf16(kf[2 * d0], qr[d0], p0, 0, 0, 0);
;         p1 = __builtin_amdgcn_mfma_f32_32x32x16_bf16(kf[2 * d0 + 1], qr[d0], p1, 0, 0, 0);
;     }
;     __builtin_amdgcn_sched_barrier(0);
;     if (LEVEL == 2) { asm volatile("" :: "v"(p0), "v"(p1)); return; }
;     if (masked) {
;         asm volatile("; masked tile" ::: "memory");
; #pragma unroll
;         for (int r = 0; r < 16; ++r) { const int kv = crow(r, hi); if (kv >= qlim) p0[r] = NEG; if (kv + 32 >= qlim) p1[r] = NEG; }
;     }
;     float rm = max3f(p0[0], p1[0], p0[1]), rm2 = max3f(p1[1], p0[2], p1[2]);
; #pragma unroll
;     for (int r = 3; r < 15; r += 2) { rm = max3f(rm, p0[r], p1[r]); rm2 = max3f(rm2, p0[r + 1], p1[r + 1]); }
;     rm = max3f(rm, p0[15], p1[15]); rm = swap_max(max3f(rm, rm2, rm2));
;     ...
;     for (int r = 0; r < 16; ++r) { p0[r] = __builtin_amdgcn_exp2f(p0[r]); p1[r] = __builtin_amdgcn_exp2f(p1[r]); sacc = fadd_s(sacc, p0[r]); sacc2 = fadd_s(sacc2, p1[r]); }
;     st.l = fadd_s(st.l, fadd_s(sacc, sacc2));
;     const u32x4 pw0 = ATT_PACK4(p0, 0, cvtpk), pw1 = ATT_PACK4(p0, 8, cvtpk), pw2 = ATT_PACK4(p1, 0, cvtpk), pw3 = ATT_PACK4(p1, 8, cvtpk);
;     __builtin_amdgcn_sched_barrier(0);
;     ...
;     pv(st.o, vf, pw0, pw1, pw2, pw3);
	v_add_f32_e32 v112, v112, v73
	v_exp_f32_e32 v75, v75
	v_add_f32_e32 v113, v113, v57
	v_exp_f32_e32 v59, v59
	v_add_f32_e32 v112, v112, v74
	v_exp_f32_e32 v76, v76
	v_add_f32_e32 v113, v113, v58
	v_exp_f32_e32 v60, v60
	v_add_f32_e32 v112, v112, v75
	v_exp_f32_e32 v77, v77
	v_add_f32_e32 v113, v113, v59
	v_exp_f32_e32 v61, v61
	v_add_f32_e32 v112, v76, v112
	v_exp_f32_e32 v78, v78
	v_add_f32_e32 v113, v60, v113
	v_exp_f32_e32 v62, v62
	v_add_f32_e32 v112, v77, v112
	v_exp_f32_e32 v79, v79
	v_add_f32_e32 v113, v61, v113
	v_exp_f32_e32 v63, v63
	v_add_f32_e32 v112, v78, v112
	v_exp_f32_e32 v80, v80
	v_add_f32_e32 v113, v62, v113
	v_exp_f32_e32 v64, v64
	v_add_f32_e32 v112, v79, v112
	v_exp_f32_e32 v81, v81
	v_add_f32_e32 v113, v63, v113
	v_exp_f32_e32 v65, v65
	v_add_f32_e32 v112, v80, v112
	v_exp_f32_e32 v82, v82
	v_add_f32_e32 v113, v64, v113
	v_exp_f32_e32 v66, v66
	v_add_f32_e32 v112, v81, v112
	v_exp_f32_e32 v83, v83
	v_add_f32_e32 v113, v65, v113
	v_exp_f32_e32 v67, v67
	v_add_f32_e32 v112, v82, v112
	v_add_f32_e32 v113, v66, v113
	v_add_f32_e32 v112, v83, v112
	v_add_f32_e32 v113, v67, v113
	v_cvt_pk_bf16_f32 v114, v72, v73
	v_add_f32_e32 v112, v112, v113
	v_cvt_pk_bf16_f32 v113, v70, v71
	v_add_f32_e32 v194, v192, v112
	v_cvt_pk_bf16_f32 v112, v68, v69
	v_cvt_pk_bf16_f32 v115, v74, v75
	v_cvt_pk_bf16_f32 v160, v76, v77
	v_cvt_pk_bf16_f32 v161, v78, v79
	v_cvt_pk_bf16_f32 v162, v80, v81
	v_cvt_pk_bf16_f32 v163, v82, v83
	v_cvt_pk_bf16_f32 v164, v164, v165
	v_cvt_pk_bf16_f32 v165, v166, v167
	v_cvt_pk_bf16_f32 v166, v56, v57
	v_cvt_pk_bf16_f32 v167, v58, v59
	v_cvt_pk_bf16_f32 v198, v60, v61
	v_cvt_pk_bf16_f32 v199, v62, v63
	v_cvt_pk_bf16_f32 v200, v64, v65
	v_cvt_pk_bf16_f32 v201, v66, v67
	s_waitcnt lgkmcnt(14)
	v_mfma_f32_32x32x16_bf16 v[68:83], v[112:115], v[52:55], v[20:35]
	s_waitcnt lgkmcnt(6)
	v_mfma_f32_32x32x16_bf16 v[52:67], v[112:115], v[96:99], v[36:51]
	v_mfma_f32_32x32x16_bf16 v[68:83], v[160:163], v[84:87], v[68:83]
	s_waitcnt lgkmcnt(4)
	v_mfma_f32_32x32x16_bf16 v[52:67], v[160:163], v[100:103], v[52:67]
	v_mfma_f32_32x32x16_bf16 v[68:83], v[164:167], v[88:91], v[68:83]
	s_waitcnt lgkmcnt(2)
	v_mfma_f32_32x32x16_bf16 v[52:67], v[164:167], v[104:107], v[52:67]
	v_mfma_f32_32x32x16_bf16 v[68:83], v[198:201], v[92:95], v[68:83]
	ds_read_b128 v[84:87], v196
	ds_read_b128 v[88:91], v196 offset:32
	ds_read_b128 v[92:95], v196 offset:64
	ds_read_b128 v[96:99], v196 offset:96
	s_waitcnt lgkmcnt(4)
	v_mfma_f32_32x32x16_bf16 v[52:67], v[198:201], v[108:111], v[52:67]
	ds_read_b128 v[100:103], v196 offset:128
	ds_read_b128 v[104:107], v196 offset:160
	ds_read_b128 v[108:111], v196 offset:192
	ds_read_b128 v[112:115], v196 offset:224
	ds_read_b128 v[160:163], v195
	ds_read_b128 v[164:167], v195 offset:512
	s_waitcnt lgkmcnt(6)
	v_mfma_f32_32x32x16_bf16 v[84:99], v[120:123], v[2:5], v[84:99]
	s_waitcnt lgkmcnt(2)
	v_mfma_f32_32x32x16_bf16 v[100:115], v[120:123], v[2:5], v[100:115]
	s_waitcnt lgkmcnt(1)
	v_mfma_f32_32x32x16_bf16 v[84:99], v[160:163], v[6:9], v[84:99]
	s_waitcnt lgkmcnt(0)
	v_mfma_f32_32x32x16_bf16 v[100:115], v[164:167], v[6:9], v[100:115]
	ds_read_b128 v[160:163], v195 offset:2048
	ds_read_b128 v[164:167], v195 offset:2560
	s_waitcnt lgkmcnt(1)
	v_mfma_f32_32x32x16_bf16 v[84:99], v[160:163], v[10:13], v[84:99]
	s_waitcnt lgkmcnt(0)
	v_mfma_f32_32x32x16_bf16 v[100:115], v[164:167], v[10:13], v[100:115]
	ds_read_b128 v[160:163], v195 offset:4096
	ds_read_b128 v[164:167], v195 offset:4608
	s_waitcnt lgkmcnt(1)
	v_mfma_f32_32x32x16_bf16 v[84:99], v[160:163], v[14:17], v[84:99]
	s_waitcnt lgkmcnt(0)
	v_mfma_f32_32x32x16_bf16 v[100:115], v[164:167], v[14:17], v[100:115]
	ds_read_b128 v[160:163], v195 offset:6144
	ds_read_b128 v[164:167], v195 offset:6656
	s_waitcnt lgkmcnt(1)
	v_mfma_f32_32x32x16_bf16 v[84:99], v[160:163], v[116:119], v[84:99]
	s_waitcnt lgkmcnt(0)
	v_mfma_f32_32x32x16_bf16 v[100:115], v[164:167], v[116:119], v[100:115]
	s_nop 11
	v_max_f32_e32 v160, v100, v100
	v_max_f32_e32 v161, v84, v84
	v_max_f32_e32 v160, v161, v160
	v_max3_f32 v161, v101, v86, v102
	v_max3_f32 v160, v160, v85, v87
	v_max3_f32 v161, v161, v88, v104
	v_max3_f32 v160, v160, v103, v89
	v_max3_f32 v161, v161, v90, v106
	v_max3_f32 v160, v160, v105, v91
	v_max3_f32 v161, v161, v92, v108
	v_max3_f32 v160, v160, v107, v93
	v_max3_f32 v161, v161, v94, v110
	v_max3_f32 v160, v160, v109, v95
	v_max3_f32 v161, v161, v96, v112
	v_max3_f32 v160, v160, v111, v97
	v_max3_f32 v161, v161, v98, v114
	v_max3_f32 v160, v160, v113, v99
	v_max3_f32 v160, v160, v115, v161
	v_mov_b32_e32 v161, v160
	s_nop 1
	v_permlane32_swap_b32_e32 v160, v161
	v_max_f32_e32 v161, v161, v161
	v_max_f32_e32 v160, v160, v160
	v_max_f32_e32 v160, v160, v161
	s_mov_b32 s2, 0x41000000
	v_cmp_lt_f32_e32 vcc, s2, v160
	s_cbranch_vccz .LBB0_976
; #define LAS __attribute__((address_space(3)))
; #define ATT_LDS_WAIT() asm volatile("s_waitcnt lgkmcnt(0)" ::: "memory")
;     ...
;     if (first || __any(rm > FOX_THR)) {
;         const float dl = first ? rm : fmaxf(rm, 0.f);
;         st.m += dl; st.mq = make_mq(st.m, hi);
; #pragma unroll
;         for (int r = 0; r < 16; ++r) { p0[r] -= dl; p1[r] -= dl; }
;         if (!first) {
;             const float f = __builtin_amdgcn_exp2f(-dl);
;             st.l *= f;
;             if (hi == 0) wsf[r32] = f;
;             ATT_LDS_WAIT();
; #pragma unroll
;             for (int g = 0; g < 4; ++g) { const f32x4 fv = *(const LAS f32x4*)(wsf + 8 * g + 4 * hi);
; #pragma unroll
;                 for (int i = 0; i < 4; ++i) { st.o[0][4 * g + i] *= fv[i]; st.o[1][4 * g + i] *= fv[i]; } }
;         }
;     }
	v_max_f32_e32 v3, v160, v160
	v_max_f32_e32 v160, 0, v3
	v_exp_f32_e64 v161, -v160
	s_and_saveexec_b64 s[2:3], s[6:7]
	ds_write_b32 v184, v161
	s_or_b64 exec, exec, s[2:3]
	v_add_f32_e32 v191, v191, v160
	v_cvt_pk_bf16_f32 v3, v191, 0
	v_lshlrev_b32_e32 v3, 16, v3
	v_sub_f32_e32 v4, v191, v3
	v_cvt_pk_bf16_f32 v162, v4, 0
	v_lshlrev_b32_e32 v162, 16, v162
	v_sub_f32_e32 v4, v4, v162
	s_waitcnt lgkmcnt(0)
	v_add_u32_e32 v197, s89, v174
	v_cvt_pk_bf16_f32 v4, v162, v4
	v_pk_add_f32 v[84:85], v[84:85], v[160:161] op_sel_hi:[1,0] neg_lo:[0,1] neg_hi:[0,1]
	v_pk_add_f32 v[100:101], v[100:101], v[160:161] op_sel_hi:[1,0] neg_lo:[0,1] neg_hi:[0,1]
	v_pk_add_f32 v[86:87], v[86:87], v[160:161] op_sel_hi:[1,0] neg_lo:[0,1] neg_hi:[0,1]
	v_pk_add_f32 v[102:103], v[102:103], v[160:161] op_sel_hi:[1,0] neg_lo:[0,1] neg_hi:[0,1]
	v_pk_add_f32 v[88:89], v[88:89], v[160:161] op_sel_hi:[1,0] neg_lo:[0,1] neg_hi:[0,1]
	v_pk_add_f32 v[104:105], v[104:105], v[160:161] op_sel_hi:[1,0] neg_lo:[0,1] neg_hi:[0,1]
	v_pk_add_f32 v[90:91], v[90:91], v[160:161] op_sel_hi:[1,0] neg_lo:[0,1] neg_hi:[0,1]
	v_pk_add_f32 v[106:107], v[106:107], v[160:161] op_sel_hi:[1,0] neg_lo:[0,1] neg_hi:[0,1]
	v_pk_add_f32 v[92:93], v[92:93], v[160:161] op_sel_hi:[1,0] neg_lo:[0,1] neg_hi:[0,1]
	v_pk_add_f32 v[108:109], v[108:109], v[160:161] op_sel_hi:[1,0] neg_lo:[0,1] neg_hi:[0,1]
	v_pk_add_f32 v[94:95], v[94:95], v[160:161] op_sel_hi:[1,0] neg_lo:[0,1] neg_hi:[0,1]
	v_pk_add_f32 v[110:111], v[110:111], v[160:161] op_sel_hi:[1,0] neg_lo:[0,1] neg_hi:[0,1]
	v_pk_add_f32 v[96:97], v[96:97], v[160:161] op_sel_hi:[1,0] neg_lo:[0,1] neg_hi:[0,1]
	v_pk_add_f32 v[112:113], v[112:113], v[160:161] op_sel_hi:[1,0] neg_lo:[0,1] neg_hi:[0,1]
	v_pk_add_f32 v[98:99], v[98:99], v[160:161] op_sel_hi:[1,0] neg_lo:[0,1] neg_hi:[0,1]
	v_pk_add_f32 v[114:115], v[114:115], v[160:161] op_sel_hi:[1,0] neg_lo:[0,1] neg_hi:[0,1]
	v_mul_f32_e32 v194, v194, v161
	ds_read_b128 v[160:163], v197
	ds_read_b128 v[164:167], v197 offset:32
	ds_read_b128 v[198:201], v197 offset:64
	ds_read_b128 v[202:205], v197 offset:96
	v_cvt_pk_bf16_f32 v3, 1.0, v3
	v_cndmask_b32_e64 v4, 0, v4, s[6:7]
	v_cndmask_b32_e64 v3, 0, v3, s[6:7]
	s_waitcnt lgkmcnt(1)
	v_pk_mul_f32 v[76:77], v[76:77], v[198:199]
	s_waitcnt lgkmcnt(0)
	v_pk_mul_f32 v[80:81], v[80:81], v[202:203]
	v_pk_mul_f32 v[72:73], v[72:73], v[164:165]
	v_pk_mul_f32 v[82:83], v[82:83], v[204:205]
	v_pk_mul_f32 v[78:79], v[78:79], v[200:201]
	v_pk_mul_f32 v[74:75], v[74:75], v[166:167]
	v_pk_mul_f32 v[70:71], v[70:71], v[162:163]
	v_pk_mul_f32 v[68:69], v[68:69], v[160:161]
	v_pk_mul_f32 v[64:65], v[64:65], v[202:203]
	v_pk_mul_f32 v[60:61], v[60:61], v[198:199]
	v_pk_mul_f32 v[56:57], v[56:57], v[164:165]
	v_pk_mul_f32 v[66:67], v[66:67], v[204:205]
	v_pk_mul_f32 v[62:63], v[62:63], v[200:201]
	v_pk_mul_f32 v[58:59], v[58:59], v[166:167]
	v_pk_mul_f32 v[54:55], v[54:55], v[162:163]
	v_pk_mul_f32 v[52:53], v[52:53], v[160:161]

; __device__ __forceinline__ void prompt_unit_fox(const Args& a, int l, int b, int h, int qb, LAS unsigned char* lds) {
;     ...
;             if (lateB) { pending = true; pslot = slot; } else fox_pair_pv(st, pp, vp);
;         } else if (jp == jpd) {
;             if (jd & 1) { fox_tile(st, kslot + 8192, vp + 8192, qr, ck0 + 64, true, true, qlim, r32, hi, wsf); fox_tile(st, kslot, vp, qr, ck0, false, false, qlim, r32, hi, wsf); }
;             else fox_tile(st, kslot, vp, qr, ck0, true, true, qlim, r32, hi, wsf);
;         }
;         slot = (slot == 2) ? 0 : slot + 1;
.LBB0_992:
	s_mov_b64 s[2:3], 0
	s_nop 15
	v_mov_b64_e32 v[20:21], v[68:69]
	v_mov_b64_e32 v[22:23], v[70:71]
	v_mov_b64_e32 v[24:25], v[72:73]
	v_mov_b64_e32 v[26:27], v[74:75]
	v_mov_b64_e32 v[28:29], v[76:77]
	v_mov_b64_e32 v[30:31], v[78:79]
	v_mov_b64_e32 v[32:33], v[80:81]
	v_mov_b64_e32 v[34:35], v[82:83]
	v_mov_b64_e32 v[36:37], v[52:53]
	v_mov_b64_e32 v[38:39], v[54:55]
	v_mov_b64_e32 v[40:41], v[56:57]
	v_mov_b64_e32 v[42:43], v[58:59]
	v_mov_b64_e32 v[44:45], v[60:61]
	v_mov_b64_e32 v[46:47], v[62:63]
	v_mov_b64_e32 v[48:49], v[64:65]
	v_mov_b64_e32 v[50:51], v[66:67]
	s_branch .LBB0_998

; __device__ __forceinline__ void prompt_unit_fox(const Args& a, int l, int b, int h, int qb, LAS unsigned char* lds) {
;     ...
;         slot = (slot == 2) ? 0 : slot + 1;
.LBB0_997:
	s_nop 10
.LBB0_998:
	s_add_i32 s33, s93, 1
	s_cmp_lg_u32 s93, 2
	s_cselect_b32 s93, s33, 0
	s_add_i32 s33, s78, -1
	s_cmp_lt_i32 s78, 1
	s_cbranch_scc1 .LBB0_1010
	v_mov_b64_e32 v[156:157], v[160:161]
	s_mov_b32 s78, s33
	v_mov_b64_e32 v[158:159], v[162:163]
	v_mov_b32_e32 v192, v194
	v_mov_b32_e32 v193, v191
	s_branch .LBB0_964

; __device__ __forceinline__ void vfrags(VFrags& v, lds_cptr vp) {
; #pragma unroll
;     ...
; }
; __device__ __forceinline__ void pv(f32x16 (&o)[2], const VFrags& v, const u32x4& pw0, const u32x4& pw1, const u32x4& pw2, const u32x4& pw3) {
;     ...
;     o[0] = __builtin_amdgcn_mfma_f32_32x32x16_bf16(__builtin_bit_cast(bf16x8, pw0), ATT_VF(0), o[0], 0, 0, 0);
;     o[1] = __builtin_amdgcn_mfma_f32_32x32x16_bf16(__builtin_bit_cast(bf16x8, pw0), ATT_VF(4), o[1], 0, 0, 0);
;     o[0] = __builtin_amdgcn_mfma_f32_32x32x16_bf16(__builtin_bit_cast(bf16x8, pw1), ATT_VF(1), o[0], 0, 0, 0);
;     o[1] = __builtin_amdgcn_mfma_f32_32x32x16_bf16(__builtin_bit_cast(bf16x8, pw1), ATT_VF(5), o[1], 0, 0, 0);
;     o[0] = __builtin_amdgcn_mfma_f32_32x32x16_bf16(__builtin_bit_cast(bf16x8, pw2), ATT_VF(2), o[0], 0, 0, 0);
;     o[1] = __builtin_amdgcn_mfma_f32_32x32x16_bf16(__builtin_bit_cast(bf16x8, pw2), ATT_VF(6), o[1], 0, 0, 0);
;     o[0] = __builtin_amdgcn_mfma_f32_32x32x16_bf16(__builtin_bit_cast(bf16x8, pw3), ATT_VF(3), o[0], 0, 0, 0);
;     o[1] = __builtin_amdgcn_mfma_f32_32x32x16_bf16(__builtin_bit_cast(bf16x8, pw3), ATT_VF(7), o[1], 0, 0, 0);
;     ...
; }
; __device__ __forceinline__ void prompt_unit_fox(const Args& a, int l, int b, int h, int qb, LAS unsigned char* lds) {
;     ...
;         slot = (slot == 2) ? 0 : slot + 1;
;     }
;     ...
;     if (pending) fox_pair_pv(st, pp, vp0 + pslot * 16384);
.LBB0_1010:
	s_nop 3
	v_mov_b64_e32 v[68:69], v[20:21]
	v_mov_b64_e32 v[70:71], v[22:23]
	v_mov_b64_e32 v[72:73], v[24:25]
	v_mov_b64_e32 v[74:75], v[26:27]
	v_mov_b64_e32 v[76:77], v[28:29]
	v_mov_b64_e32 v[78:79], v[30:31]
	v_mov_b64_e32 v[80:81], v[32:33]
	v_mov_b64_e32 v[82:83], v[34:35]
	v_mov_b64_e32 v[52:53], v[36:37]
	v_mov_b64_e32 v[54:55], v[38:39]
	v_mov_b64_e32 v[56:57], v[40:41]
	v_mov_b64_e32 v[58:59], v[42:43]
	v_mov_b64_e32 v[60:61], v[44:45]
	v_mov_b64_e32 v[62:63], v[46:47]
	v_mov_b64_e32 v[64:65], v[48:49]
	v_mov_b64_e32 v[66:67], v[50:51]
	s_and_b64 vcc, exec, s[2:3]
	s_cbranch_vccz .LBB0_1012
	v_lshl_add_u32 v2, s75, 14, v175
	ds_read_b64_tr_b16 v[6:7], v2 offset:57344
	ds_read_b64_tr_b16 v[8:9], v2 offset:57856
	ds_read_b64_tr_b16 v[10:11], v2 offset:58368
	ds_read_b64_tr_b16 v[12:13], v2 offset:58880
	s_waitcnt lgkmcnt(2)
	v_mfma_f32_32x32x16_bf16 v[68:83], v[152:155], v[6:9], v[68:83]
	ds_read_b64_tr_b16 v[6:7], v2 offset:61440
	ds_read_b64_tr_b16 v[8:9], v2 offset:61952
	ds_read_b64_tr_b16 v[14:15], v2 offset:62464
	ds_read_b64_tr_b16 v[16:17], v2 offset:62976
	s_waitcnt lgkmcnt(2)
	v_mfma_f32_32x32x16_bf16 v[52:67], v[152:155], v[6:9], v[52:67]
	v_mfma_f32_32x32x16_bf16 v[68:83], v[148:151], v[10:13], v[68:83]
	ds_read_b64_tr_b16 v[6:7], v2 offset:59392
	ds_read_b64_tr_b16 v[8:9], v2 offset:59904
	ds_read_b64_tr_b16 v[10:11], v2 offset:60416
	ds_read_b64_tr_b16 v[12:13], v2 offset:60928
	s_waitcnt lgkmcnt(4)
	v_mfma_f32_32x32x16_bf16 v[52:67], v[148:151], v[14:17], v[52:67]
	s_waitcnt lgkmcnt(2)
	v_mfma_f32_32x32x16_bf16 v[68:83], v[144:147], v[6:9], v[68:83]
	ds_read_b64_tr_b16 v[6:7], v2 offset:63488
	ds_read_b64_tr_b16 v[8:9], v2 offset:64000
	ds_read_b64_tr_b16 v[14:15], v2 offset:64512
	ds_read_b64_tr_b16 v[16:17], v2 offset:65024
	s_waitcnt lgkmcnt(2)
	v_mfma_f32_32x32x16_bf16 v[52:67], v[144:147], v[6:9], v[52:67]
	v_mfma_f32_32x32x16_bf16 v[68:83], v[140:143], v[10:13], v[68:83]
	ds_read_b64_tr_b16 v[6:7], v2 offset:49152
	ds_read_b64_tr_b16 v[8:9], v2 offset:49664
	ds_read_b64_tr_b16 v[10:11], v2 offset:50176
	ds_read_b64_tr_b16 v[12:13], v2 offset:50688
	s_waitcnt lgkmcnt(4)
	v_mfma_f32_32x32x16_bf16 v[52:67], v[140:143], v[14:17], v[52:67]
	s_waitcnt lgkmcnt(2)
	v_mfma_f32_32x32x16_bf16 v[68:83], v[136:139], v[6:9], v[68:83]
	ds_read_b64_tr_b16 v[6:7], v2 offset:53248
	ds_read_b64_tr_b16 v[8:9], v2 offset:53760
	ds_read_b64_tr_b16 v[14:15], v2 offset:54272
	ds_read_b64_tr_b16 v[16:17], v2 offset:54784
	s_waitcnt lgkmcnt(2)
	v_mfma_f32_32x32x16_bf16 v[52:67], v[136:139], v[6:9], v[52:67]
	v_mfma_f32_32x32x16_bf16 v[68:83], v[132:135], v[10:13], v[68:83]
	ds_read_b64_tr_b16 v[6:7], v2 offset:51200
	ds_read_b64_tr_b16 v[8:9], v2 offset:51712
	ds_read_b64_tr_b16 v[10:11], v2 offset:52224
	ds_read_b64_tr_b16 v[12:13], v2 offset:52736
	s_waitcnt lgkmcnt(4)
	v_mfma_f32_32x32x16_bf16 v[52:67], v[132:135], v[14:17], v[52:67]
	s_waitcnt lgkmcnt(2)
	v_mfma_f32_32x32x16_bf16 v[68:83], v[128:131], v[6:9], v[68:83]
	ds_read_b64_tr_b16 v[6:7], v2 offset:55296
	ds_read_b64_tr_b16 v[8:9], v2 offset:55808
	ds_read_b64_tr_b16 v[14:15], v2 offset:56320
	ds_read_b64_tr_b16 v[16:17], v2 offset:56832
	s_waitcnt lgkmcnt(2)
	v_mfma_f32_32x32x16_bf16 v[52:67], v[128:131], v[6:9], v[52:67]
	v_mfma_f32_32x32x16_bf16 v[68:83], v[124:127], v[10:13], v[68:83]
	s_waitcnt lgkmcnt(0)
	v_mfma_f32_32x32x16_bf16 v[52:67], v[124:127], v[14:17], v[52:67]

; #define LAS __attribute__((address_space(3)))
; __global__ void __launch_bounds__(NTHR, 2) fwd(Args a_in) {
;     extern __shared__ __attribute__((aligned(16))) unsigned char lds_raw[];
;     LAS unsigned char* lds = (LAS unsigned char*)lds_raw;
;     volatile LAS unsigned* MISC = (volatile LAS unsigned*)(lds + MISC_OFF);
;     if (threadIdx.x < 32) MISC[threadIdx.x] = 0u;
;     __syncthreads();
;     const KArgs kp0 = (KArgs)__builtin_amdgcn_kernarg_segment_ptr();
;     unsigned* ctl = (unsigned*)(a_in.ws + WS_CTL);
;     const bool multi = (a_in.ph_hi - a_in.ph_lo) > 1;
;     XcdBarrier bar; bar.bar = ctl + CW_BAR; bar.x = 0; bar.st = nullptr;
;     if (multi) bar = xcd_barrier_post(ctl + CW_BAR, MISC + 8);
;     const int lo = a_in.ph_lo, hi = a_in.ph_hi;
;     ...
;     run_layer<0>(kp0, lds, bar, lo, hi);
;     run_layer<1>(kp0, lds, bar, lo, hi);
;     if (IN(9)) { FRESH_IDS(); phase_final(a, gwave, nwaves, lane); if (PROBE_DOUBLE == 10) phase_final(a, gwave, nwaves, lane); }
;     ...
; }
	.amdhsa_kernel _Z3fwd4Args
		.amdhsa_group_segment_fixed_size 0
		.amdhsa_private_segment_fixed_size 0
		.amdhsa_kernarg_size 392
		.amdhsa_user_sgpr_count 2
		.amdhsa_user_sgpr_dispatch_ptr 0
		.amdhsa_user_sgpr_queue_ptr 0
		.amdhsa_user_sgpr_kernarg_segment_ptr 1
		.amdhsa_user_sgpr_dispatch_id 0
		.amdhsa_user_sgpr_kernarg_preload_length 0
		.amdhsa_user_sgpr_kernarg_preload_offset 0
		.amdhsa_user_sgpr_private_segment_size 0
		.amdhsa_uses_dynamic_stack 0
		.amdhsa_enable_private_segment 0
		.amdhsa_system_sgpr_workgroup_id_x 1
		.amdhsa_system_sgpr_workgroup_id_y 0
		.amdhsa_system_sgpr_workgroup_id_z 0
		.amdhsa_system_sgpr_workgroup_info 0
		.amdhsa_system_vgpr_workitem_id 0
		.amdhsa_next_free_vgpr 248
		.amdhsa_next_free_sgpr 98
		.amdhsa_accum_offset 248
		.amdhsa_reserve_vcc 1
		.amdhsa_float_round_mode_32 0
		.amdhsa_float_round_mode_16_64 0
		.amdhsa_float_denorm_mode_32 3
		.amdhsa_float_denorm_mode_16_64 3
		.amdhsa_dx10_clamp 1
		.amdhsa_ieee_mode 1
		.amdhsa_fp16_overflow 0
		.amdhsa_tg_split 0
		.amdhsa_exception_fp_ieee_invalid_op 0
		.amdhsa_exception_fp_denorm_src 0
		.amdhsa_exception_fp_ieee_div_zero 0
		.amdhsa_exception_fp_ieee_overflow 0
		.amdhsa_exception_fp_ieee_underflow 0
		.amdhsa_exception_fp_ieee_inexact 0
		.amdhsa_exception_int_div_zero 0
	.end_amdhsa_kernel

; #define LAS __attribute__((address_space(3)))
; __global__ void __launch_bounds__(NTHR, 2) fwd(Args a_in) {
;     extern __shared__ __attribute__((aligned(16))) unsigned char lds_raw[];
;     LAS unsigned char* lds = (LAS unsigned char*)lds_raw;
;     volatile LAS unsigned* MISC = (volatile LAS unsigned*)(lds + MISC_OFF);
;     if (threadIdx.x < 32) MISC[threadIdx.x] = 0u;
;     __syncthreads();
;     const KArgs kp0 = (KArgs)__builtin_amdgcn_kernarg_segment_ptr();
;     unsigned* ctl = (unsigned*)(a_in.ws + WS_CTL);
;     const bool multi = (a_in.ph_hi - a_in.ph_lo) > 1;
;     XcdBarrier bar; bar.bar = ctl + CW_BAR; bar.x = 0; bar.st = nullptr;
;     if (multi) bar = xcd_barrier_post(ctl + CW_BAR, MISC + 8);
;     const int lo = a_in.ph_lo, hi = a_in.ph_hi;
;     ...
;     run_layer<0>(kp0, lds, bar, lo, hi);
;     run_layer<1>(kp0, lds, bar, lo, hi);
;     if (IN(9)) { FRESH_IDS(); phase_final(a, gwave, nwaves, lane); if (PROBE_DOUBLE == 10) phase_final(a, gwave, nwaves, lane); }
;     ...
; }
amdhsa.kernels:
  - .agpr_count:     0
    .args:
      - .offset:         0
        .size:           136
        .value_kind:     by_value
      - .offset:         136
        .size:           4
        .value_kind:     hidden_block_count_x
      - .offset:         140
        .size:           4
        .value_kind:     hidden_block_count_y
      - .offset:         144
        .size:           4
        .value_kind:     hidden_block_count_z
      - .offset:         148
        .size:           2
        .value_kind:     hidden_group_size_x
      - .offset:         150
        .size:           2
        .value_kind:     hidden_group_size_y
      - .offset:         152
        .size:           2
        .value_kind:     hidden_group_size_z
      - .offset:         154
        .size:           2
        .value_kind:     hidden_remainder_x
      - .offset:         156
        .size:           2
        .value_kind:     hidden_remainder_y
      - .offset:         158
        .size:           2
        .value_kind:     hidden_remainder_z
      - .offset:         176
        .size:           8
        .value_kind:     hidden_global_offset_x
      - .offset:         184
        .size:           8
        .value_kind:     hidden_global_offset_y
      - .offset:         192
        .size:           8
        .value_kind:     hidden_global_offset_z
      - .offset:         200
        .size:           2
        .value_kind:     hidden_grid_dims
      - .offset:         256
        .size:           4
        .value_kind:     hidden_dynamic_lds_size
    .group_segment_fixed_size: 0
    .kernarg_segment_align: 8
    .kernarg_segment_size: 392
    .language:       OpenCL C
    .language_version:
      - 2
      - 0
    .max_flat_workgroup_size: 512
    .name:           _Z3fwd4Args
    .private_segment_fixed_size: 0
    .sgpr_count:     104
    .sgpr_spill_count: 137
    .symbol:         _Z3fwd4Args.kd
    .uniform_work_group_size: 1
    .uses_dynamic_stack: false
    .vgpr_count:     248
    .vgpr_spill_count: 0
    .wavefront_size: 64
